# attention steps: P fragments packed once per key pair and split by per-lane half-word masks (2 cvt + 4 and instead of 8 cndmask + 4 cvt)
# speedup vs baseline: 1.0034x; 1.0005x over previous
.LBB0_399:
	s_add_i32 s97, s38, s92
	s_lshl_b32 s38, s97, 6
	s_add_i32 s38, s38, s39
	v_add_u32_e32 v128, s38, v146
	s_lshl_b32 s38, s71, 1
	s_mov_b32 s39, s61
	v_ashrrev_i32_e32 v129, 31, v128
	v_lshl_add_u64 v[0:1], v[116:117], 0, s[38:39]
	v_lshlrev_b64 v[2:3], 10, v[128:129]
	v_add_u32_e32 v126, 16, v128
	v_lshl_add_u64 v[2:3], v[0:1], 0, v[2:3]
	v_ashrrev_i32_e32 v127, 31, v126
	global_load_dwordx4 v[80:83], v[2:3], off
	global_load_dwordx4 v[84:87], v[2:3], off offset:64
	v_lshlrev_b64 v[2:3], 10, v[126:127]
	v_add_u32_e32 v122, 32, v128
	v_lshl_add_u64 v[2:3], v[0:1], 0, v[2:3]
	v_ashrrev_i32_e32 v123, 31, v122
	global_load_dwordx4 v[88:91], v[2:3], off
	global_load_dwordx4 v[92:95], v[2:3], off offset:64
	v_lshlrev_b64 v[2:3], 10, v[122:123]
	v_add_u32_e32 v120, 48, v128
	v_lshl_add_u64 v[2:3], v[0:1], 0, v[2:3]
	v_ashrrev_i32_e32 v121, 31, v120
	global_load_dwordx4 v[96:99], v[2:3], off
	global_load_dwordx4 v[100:103], v[2:3], off offset:64
	v_lshlrev_b64 v[2:3], 10, v[120:121]
	v_lshl_add_u64 v[0:1], v[0:1], 0, v[2:3]
	global_load_dwordx4 v[104:107], v[0:1], off
	global_load_dwordx4 v[108:111], v[0:1], off offset:64
	v_mov_b32_e32 v131, 0
	s_andn2_b64 vcc, exec, s[72:73]
	v_mov_b32_e32 v130, 0
	v_mov_b32_e32 v125, 0
	v_mov_b32_e32 v124, 0
	v_mov_b32_e32 v63, 0
	v_mov_b32_e32 v62, 0
	v_mov_b32_e32 v61, 0
	v_mov_b32_e32 v60, 0
	v_mov_b32_e32 v59, 0
	v_mov_b32_e32 v58, 0
	v_mov_b32_e32 v57, 0
	v_mov_b32_e32 v56, 0
	v_mov_b32_e32 v55, 0
	v_mov_b32_e32 v54, 0
	v_mov_b32_e32 v53, 0
	v_mov_b32_e32 v52, 0
	v_mov_b32_e32 v51, 0
	v_mov_b32_e32 v50, 0
	v_mov_b32_e32 v49, 0
	v_mov_b32_e32 v48, 0
	v_mov_b32_e32 v47, 0
	v_mov_b32_e32 v46, 0
	v_mov_b32_e32 v45, 0
	v_mov_b32_e32 v44, 0
	v_mov_b32_e32 v43, 0
	v_mov_b32_e32 v42, 0
	v_mov_b32_e32 v41, 0
	v_mov_b32_e32 v40, 0
	v_mov_b32_e32 v39, 0
	v_mov_b32_e32 v38, 0
	v_mov_b32_e32 v37, 0
	v_mov_b32_e32 v36, 0
	v_mov_b32_e32 v35, 0
	v_mov_b32_e32 v34, 0
	v_mov_b32_e32 v33, 0
	v_mov_b32_e32 v32, 0
	v_mov_b32_e32 v31, 0
	v_mov_b32_e32 v30, 0
	v_mov_b32_e32 v29, 0
	v_mov_b32_e32 v28, 0
	v_mov_b32_e32 v27, 0
	v_mov_b32_e32 v26, 0
	v_mov_b32_e32 v25, 0
	v_mov_b32_e32 v24, 0
	v_mov_b32_e32 v23, 0
	v_mov_b32_e32 v22, 0
	v_mov_b32_e32 v21, 0
	v_mov_b32_e32 v20, 0
	v_mov_b32_e32 v19, 0
	v_mov_b32_e32 v18, 0
	v_mov_b32_e32 v17, 0
	v_mov_b32_e32 v16, 0
	v_mov_b32_e32 v15, 0
	v_mov_b32_e32 v14, 0
	v_mov_b32_e32 v13, 0
	v_mov_b32_e32 v12, 0
	v_mov_b32_e32 v11, 0
	v_mov_b32_e32 v10, 0
	v_mov_b32_e32 v9, 0
	v_mov_b32_e32 v8, 0
	v_mov_b32_e32 v7, 0
	v_mov_b32_e32 v6, 0
	v_mov_b32_e32 v5, 0
	v_mov_b32_e32 v4, 0
	v_mov_b32_e32 v3, 0
	v_mov_b32_e32 v2, 0
	v_mov_b32_e32 v1, 0
	v_mov_b32_e32 v0, 0
	v_mov_b32_e32 v241, 0xffff
	v_mov_b32_e32 v242, 0xffff0000
	v_cndmask_b32_e64 v243, 0, v241, s[20:21]
	v_cndmask_b32_e64 v244, v242, 0, s[10:11]
	v_or_b32_e32 v225, v243, v244
	v_cndmask_b32_e64 v243, v241, 0, s[20:21]
	v_cndmask_b32_e64 v244, 0, v242, s[10:11]
	v_or_b32_e32 v226, v243, v244
	v_cndmask_b32_e64 v243, v241, 0, s[12:13]
	v_cndmask_b32_e64 v244, v242, 0, s[14:15]
	v_or_b32_e32 v227, v243, v244
	v_cndmask_b32_e64 v243, 0, v241, s[12:13]
	v_cndmask_b32_e64 v244, 0, v242, s[14:15]
	v_or_b32_e32 v228, v243, v244
	v_cndmask_b32_e64 v243, v241, 0, s[16:17]
	v_cndmask_b32_e64 v244, v242, 0, s[18:19]
	v_or_b32_e32 v229, v243, v244
	v_cndmask_b32_e64 v243, 0, v241, s[16:17]
	v_cndmask_b32_e64 v244, 0, v242, s[18:19]
	v_or_b32_e32 v230, v243, v244
	v_cndmask_b32_e64 v243, v241, 0, s[6:7]
	v_cndmask_b32_e64 v244, v242, 0, s[8:9]
	v_or_b32_e32 v231, v243, v244
	v_cndmask_b32_e64 v243, 0, v241, s[6:7]
	v_cndmask_b32_e64 v244, 0, v242, s[8:9]
	v_or_b32_e32 v232, v243, v244
	v_cndmask_b32_e64 v243, 0, v241, s[2:3]
	v_cndmask_b32_e64 v244, 0, v242, s[4:5]
	v_or_b32_e32 v233, v243, v244
	v_cndmask_b32_e64 v243, v241, 0, s[2:3]
	v_cndmask_b32_e64 v244, v242, 0, s[4:5]
	v_or_b32_e32 v234, v243, v244
	v_cndmask_b32_e64 v243, v241, 0, s[22:23]
	v_cndmask_b32_e64 v244, v242, 0, s[24:25]
	v_or_b32_e32 v235, v243, v244
	v_cndmask_b32_e64 v243, 0, v241, s[22:23]
	v_cndmask_b32_e64 v244, 0, v242, s[24:25]
	v_or_b32_e32 v236, v243, v244
	v_cndmask_b32_e64 v243, v241, 0, s[26:27]
	v_cndmask_b32_e64 v244, v242, 0, s[28:29]
	v_or_b32_e32 v237, v243, v244
	v_cndmask_b32_e64 v243, 0, v241, s[26:27]
	v_cndmask_b32_e64 v244, 0, v242, s[28:29]
	v_or_b32_e32 v238, v243, v244
	v_cndmask_b32_e64 v243, v241, 0, s[30:31]
	v_cndmask_b32_e64 v244, v242, 0, s[34:35]
	v_or_b32_e32 v239, v243, v244
	v_cndmask_b32_e64 v243, 0, v241, s[30:31]
	v_cndmask_b32_e64 v244, 0, v242, s[34:35]
	v_or_b32_e32 v240, v243, v244
	s_waitcnt vmcnt(9)
	ds_write_b128 v157, v[64:67]
	s_waitcnt vmcnt(8)
	ds_write_b128 v157, v[68:71] offset:9216
	s_waitcnt lgkmcnt(0)
	s_barrier
	s_cbranch_vccnz .LBB0_416
	s_max_i32 s38, s97, 4
	s_add_i32 s38, s38, -4
	s_min_u32 s38, s38, s70
	s_mov_b32 s71, s61
	v_mov_b32_e32 v133, v113
	s_add_i32 s39, s38, 8
	v_mov_b32_e32 v0, s70
	v_cmp_lt_u64_e32 vcc, s[70:71], v[132:133]
	s_add_u32 s70, s80, s60
	v_mov_b32_e32 v1, v113
	v_cndmask_b32_e32 v2, v132, v0, vcc
	v_lshlrev_b32_e32 v0, 16, v2
	s_addc_u32 s71, s81, 0
	v_lshl_add_u64 v[0:1], s[70:71], 0, v[0:1]
	v_lshl_add_u64 v[132:133], v[0:1], 0, v[134:135]
	v_lshlrev_b32_e32 v0, 7, v2
	v_mov_b32_e32 v1, v113
	s_mul_i32 s72, s95, 0x780
	v_lshlrev_b32_e32 v2, 1, v136
	v_mov_b32_e32 v3, v113
	v_lshl_add_u64 v[0:1], s[68:69], 0, v[0:1]
	s_lshl_b32 s68, s89, 7
	v_lshl_add_u64 v[134:135], v[0:1], 0, v[2:3]
	s_add_i32 s72, s72, s68
	s_lshl_b32 s68, s97, 7
	v_mov_b32_e32 v2, v113
	s_sub_i32 s68, s72, s68
	v_mov_b32_e32 v124, v113
	v_mov_b32_e32 v125, v113
	v_mov_b32_e32 v0, v113
	v_mov_b32_e32 v1, v113
	v_mov_b64_e32 v[6:7], v[2:3]
	v_mov_b64_e32 v[10:11], v[2:3]
	v_mov_b64_e32 v[14:15], v[2:3]
	v_mov_b64_e32 v[18:19], v[2:3]
	v_mov_b64_e32 v[22:23], v[2:3]
	v_mov_b64_e32 v[26:27], v[2:3]
	v_mov_b64_e32 v[30:31], v[2:3]
	v_mov_b64_e32 v[34:35], v[2:3]
	v_mov_b64_e32 v[38:39], v[2:3]
	v_mov_b64_e32 v[42:43], v[2:3]
	v_mov_b64_e32 v[46:47], v[2:3]
	v_mov_b64_e32 v[50:51], v[2:3]
	v_mov_b64_e32 v[54:55], v[2:3]
	v_mov_b64_e32 v[58:59], v[2:3]
	v_mov_b64_e32 v[62:63], v[2:3]
	s_add_i32 s60, s89, 3
	s_add_i32 s70, s68, 0
	v_mov_b64_e32 v[4:5], v[0:1]
	v_mov_b64_e32 v[8:9], v[0:1]
	v_mov_b64_e32 v[12:13], v[0:1]
	v_mov_b64_e32 v[16:17], v[0:1]
	v_mov_b64_e32 v[20:21], v[0:1]
	v_mov_b64_e32 v[24:25], v[0:1]
	v_mov_b64_e32 v[28:29], v[0:1]
	v_mov_b64_e32 v[32:33], v[0:1]
	v_mov_b64_e32 v[36:37], v[0:1]
	v_mov_b64_e32 v[40:41], v[0:1]
	v_mov_b64_e32 v[44:45], v[0:1]
	v_mov_b64_e32 v[48:49], v[0:1]
	v_mov_b64_e32 v[52:53], v[0:1]
	v_mov_b64_e32 v[56:57], v[0:1]
	v_mov_b64_e32 v[60:61], v[0:1]
	v_mov_b64_e32 v[130:131], v[124:125]
	s_branch .LBB0_403

.LBB0_405:
	s_add_i32 s72, s60, -3
	s_cmp_ge_u32 s72, s38
	s_cselect_b64 s[68:69], -1, 0
	s_cmp_lt_u32 s72, s39
	s_cselect_b64 vcc, -1, 0
	s_and_b64 s[68:69], s[68:69], vcc
	s_andn2_b64 vcc, exec, s[68:69]
	s_cbranch_vccnz .LBB0_407
	v_add_u32_e32 v178, v150, v149
	v_add_u32_e32 v181, 0x2000, v178
	v_add_u32_e32 v218, 0x2800, v178
	v_add_u32_e32 v219, 0x3000, v178
	v_add_u32_e32 v178, v150, v151
	v_add_u32_e32 v119, v148, v149
	v_add_u32_e32 v136, s70, v152
	v_add_u32_sdwa v163, s70, v143 dst_sel:DWORD dst_unused:UNUSED_PAD src0_sel:DWORD src1_sel:BYTE_2
	v_add_u32_sdwa v165, s70, v143 dst_sel:DWORD dst_unused:UNUSED_PAD src0_sel:DWORD src1_sel:BYTE_3
	v_add_u32_e32 v220, 0x2000, v178
	v_add_u32_sdwa v179, s70, v141 dst_sel:DWORD dst_unused:UNUSED_PAD src0_sel:DWORD src1_sel:BYTE_1
	ds_read_b128 v[158:161], v119
	ds_read_b128 v[166:169], v119 offset:64
	ds_read_b128 v[170:173], v119 offset:2304
	ds_read_b128 v[174:177], v119 offset:2368
	v_add_u32_e32 v162, s70, v153
	ds_read_b64 v[182:183], v181 offset:1024
	ds_read_b64 v[184:185], v181 offset:1056
	ds_read_b64 v[186:187], v218 offset:1280
	ds_read_b64 v[188:189], v218 offset:1312
	ds_read_b64 v[190:191], v219 offset:1536
	ds_read_b64 v[192:193], v219 offset:1568
	ds_read_b64 v[194:195], v220 offset:1024
	ds_read_b64 v[196:197], v220 offset:1056
	ds_read_b128 v[198:201], v119 offset:1152
	ds_read_b128 v[202:205], v119 offset:1216
	ds_read_b128 v[206:209], v119 offset:3456
	ds_read_b128 v[210:213], v119 offset:3520
	v_add_u32_e32 v178, s70, v155
	v_add_u32_sdwa v214, s70, v142 dst_sel:DWORD dst_unused:UNUSED_PAD src0_sel:DWORD src1_sel:BYTE_2
	v_add_u32_sdwa v215, s70, v142 dst_sel:DWORD dst_unused:UNUSED_PAD src0_sel:DWORD src1_sel:BYTE_3
	ds_read_b32 v136, v136 offset:41856
	ds_read_b32 v216, v162 offset:41856
	ds_read_b32 v163, v163 offset:41856
	ds_read_b32 v165, v165 offset:41856
	ds_read_b32 v217, v178 offset:41856
	ds_read_b32 v179, v179 offset:41856
	ds_read_b32 v221, v214 offset:41856
	ds_read_b32 v222, v215 offset:41856
	s_setprio 1
	s_waitcnt vmcnt(7) lgkmcnt(15)
	v_mfma_f32_16x16x32_bf16 v[158:161], v[158:161], v[80:83], 0
	s_waitcnt vmcnt(6)
	v_mfma_f32_16x16x32_bf16 v[158:161], v[166:169], v[84:87], v[158:161]
	v_mfma_f32_16x16x32_bf16 v[166:169], v[170:173], v[80:83], 0
	v_mfma_f32_16x16x32_bf16 v[166:169], v[174:177], v[84:87], v[166:169]
	s_setprio 0
	s_nop 6
	v_cndmask_b32_e64 v158, v166, v158, s[20:21]
	s_waitcnt lgkmcnt(7)
	v_add_f32_e32 v136, v136, v158
	v_exp_f32_e32 v162, v136
	v_cndmask_b32_e64 v136, v159, v167, s[10:11]
	v_cndmask_b32_e64 v159, v160, v168, s[12:13]
	s_waitcnt lgkmcnt(5)
	v_add_f32_e32 v159, v163, v159
	v_add_f32_e32 v136, v216, v136
	v_exp_f32_e32 v214, v159
	v_cndmask_b32_e64 v159, v161, v169, s[14:15]
	v_exp_f32_e32 v178, v136
	s_waitcnt lgkmcnt(4)
	v_add_f32_e32 v159, v165, v159
	v_exp_f32_e32 v216, v159
	s_nop 0
	v_cvt_pk_bf16_f32 v243, v162, v178
	v_cvt_pk_bf16_f32 v244, v214, v216
	v_and_b32_e32 v158, v243, v225
	v_and_b32_e32 v160, v243, v226
	v_and_b32_e32 v159, v244, v227
	v_and_b32_e32 v161, v244, v228
	s_setprio 1
	v_mfma_f32_16x16x32_bf16 v[60:63], v[182:185], v[158:161], v[60:63]
	v_mfma_f32_16x16x32_bf16 v[56:59], v[186:189], v[158:161], v[56:59]
	v_mfma_f32_16x16x32_bf16 v[52:55], v[190:193], v[158:161], v[52:55]
	v_mfma_f32_16x16x32_bf16 v[48:51], v[194:197], v[158:161], v[48:51]
	s_setprio 0
	ds_read_b64 v[158:159], v181 offset:1040
	ds_read_b64 v[160:161], v181 offset:1072
	ds_read_b64 v[166:167], v218 offset:1296
	ds_read_b64 v[168:169], v218 offset:1328
	ds_read_b64 v[170:171], v219 offset:1552
	ds_read_b64 v[172:173], v219 offset:1584
	ds_read_b64 v[174:175], v220 offset:1040
	ds_read_b64 v[176:177], v220 offset:1072
	ds_read_b128 v[182:185], v119 offset:3456
	ds_read_b128 v[186:189], v119 offset:3520
	ds_read_b128 v[190:193], v119 offset:5760
	ds_read_b128 v[194:197], v119 offset:5824
	v_add_u32_e32 v136, s70, v156
	v_add_u32_sdwa v165, s70, v140 dst_sel:DWORD dst_unused:UNUSED_PAD src0_sel:DWORD src1_sel:BYTE_2
	v_add_u32_sdwa v163, s70, v139 dst_sel:DWORD dst_unused:UNUSED_PAD src0_sel:DWORD src1_sel:BYTE_1
	v_add_u32_sdwa v215, s70, v140 dst_sel:DWORD dst_unused:UNUSED_PAD src0_sel:DWORD src1_sel:BYTE_3
	ds_read_b32 v136, v136 offset:41856
	ds_read_b32 v223, v163 offset:41856
	ds_read_b32 v165, v165 offset:41856
	ds_read_b32 v224, v215 offset:41856
	s_setprio 1
	s_waitcnt vmcnt(5)
	v_mfma_f32_16x16x32_bf16 v[198:201], v[198:201], v[88:91], 0
	s_waitcnt vmcnt(4)
	v_mfma_f32_16x16x32_bf16 v[198:201], v[202:205], v[92:95], v[198:201]
	v_mfma_f32_16x16x32_bf16 v[202:205], v[206:209], v[88:91], 0
	v_mfma_f32_16x16x32_bf16 v[202:205], v[210:213], v[92:95], v[202:205]
	s_setprio 0
	s_nop 6
	v_cndmask_b32_e64 v163, v198, v202, s[16:17]
	s_waitcnt lgkmcnt(15)
	v_add_f32_e32 v163, v217, v163
	v_cndmask_b32_e64 v198, v199, v203, s[18:19]
	v_cndmask_b32_e64 v200, v200, v204, s[6:7]
	v_exp_f32_e32 v163, v163
	v_add_f32_e32 v179, v179, v198
	s_waitcnt lgkmcnt(15)
	v_add_f32_e32 v200, v221, v200
	v_exp_f32_e32 v179, v179
	v_exp_f32_e32 v215, v200
	v_cndmask_b32_e64 v200, v201, v205, s[8:9]
	s_waitcnt lgkmcnt(15)
	v_add_f32_e32 v200, v222, v200
	v_exp_f32_e32 v217, v200
	s_nop 0
	v_cvt_pk_bf16_f32 v243, v163, v179
	v_cvt_pk_bf16_f32 v244, v215, v217
	v_pk_add_f32 v[162:163], v[162:163], 0 op_sel_hi:[1,0]
	v_pk_add_f32 v[162:163], v[178:179], v[162:163]
	v_pk_add_f32 v[162:163], v[214:215], v[162:163]
	v_pk_add_f32 v[162:163], v[216:217], v[162:163]
	v_pk_add_f32 v[130:131], v[130:131], v[162:163]
	v_and_b32_e32 v198, v243, v229
	v_and_b32_e32 v200, v243, v230
	v_and_b32_e32 v199, v244, v231
	v_and_b32_e32 v201, v244, v232
	s_setprio 1
	s_waitcnt lgkmcnt(14)
	v_mfma_f32_16x16x32_bf16 v[44:47], v[158:161], v[198:201], v[44:47]
	s_waitcnt lgkmcnt(12)
	v_mfma_f32_16x16x32_bf16 v[40:43], v[166:169], v[198:201], v[40:43]
	s_waitcnt lgkmcnt(10)
	v_mfma_f32_16x16x32_bf16 v[36:39], v[170:173], v[198:201], v[36:39]
	s_waitcnt lgkmcnt(8)
	v_mfma_f32_16x16x32_bf16 v[32:35], v[174:177], v[198:201], v[32:35]
	s_setprio 0
	ds_read_b64 v[158:159], v181 offset:1072
	ds_read_b64 v[160:161], v181 offset:1104
	ds_read_b64 v[166:167], v218 offset:1328
	ds_read_b64 v[168:169], v218 offset:1360
	ds_read_b64 v[170:171], v219 offset:1584
	ds_read_b64 v[172:173], v219 offset:1616
	ds_read_b64 v[174:175], v220 offset:1072
	ds_read_b64 v[176:177], v220 offset:1104
	ds_read_b128 v[198:201], v119 offset:4608
	ds_read_b128 v[202:205], v119 offset:4672
	v_add_u32_e32 v119, v148, v151
	ds_read_b128 v[206:209], v119
	ds_read_b128 v[210:213], v119 offset:64
	v_add_u32_e32 v119, s70, v154
	v_add_u32_sdwa v162, s70, v144 dst_sel:DWORD dst_unused:UNUSED_PAD src0_sel:DWORD src1_sel:BYTE_1
	v_add_u32_sdwa v163, s70, v145 dst_sel:DWORD dst_unused:UNUSED_PAD src0_sel:DWORD src1_sel:BYTE_2
	v_add_u32_sdwa v178, s70, v145 dst_sel:DWORD dst_unused:UNUSED_PAD src0_sel:DWORD src1_sel:BYTE_3
	ds_read_b32 v119, v119 offset:41856
	ds_read_b32 v179, v162 offset:41856
	ds_read_b32 v214, v163 offset:41856
	ds_read_b32 v215, v178 offset:41856
	s_setprio 1
	s_waitcnt vmcnt(3) lgkmcnt(15)
	v_mfma_f32_16x16x32_bf16 v[182:185], v[182:185], v[96:99], 0
	s_waitcnt vmcnt(2)
	v_mfma_f32_16x16x32_bf16 v[182:185], v[186:189], v[100:103], v[182:185]
	v_mfma_f32_16x16x32_bf16 v[186:189], v[190:193], v[96:99], 0
	v_mfma_f32_16x16x32_bf16 v[186:189], v[194:197], v[100:103], v[186:189]
	s_setprio 0
	s_nop 6
	v_cndmask_b32_e64 v162, v186, v182, s[2:3]
	v_add_f32_e32 v136, v136, v162
	v_exp_f32_e32 v162, v136
	v_cndmask_b32_e64 v136, v187, v183, s[4:5]
	v_cndmask_b32_e64 v183, v184, v188, s[22:23]
	s_waitcnt lgkmcnt(15)
	v_add_f32_e32 v165, v165, v183
	v_exp_f32_e32 v190, v165
	v_cndmask_b32_e64 v165, v185, v189, s[24:25]
	v_add_f32_e32 v136, v223, v136
	s_waitcnt lgkmcnt(15)
	v_add_f32_e32 v165, v224, v165
	v_exp_f32_e32 v178, v136
	v_exp_f32_e32 v192, v165
	s_nop 0
	v_cvt_pk_bf16_f32 v243, v162, v178
	v_cvt_pk_bf16_f32 v244, v190, v192
	v_and_b32_e32 v182, v243, v233
	v_and_b32_e32 v184, v243, v234
	v_and_b32_e32 v183, v244, v235
	v_and_b32_e32 v185, v244, v236
	s_setprio 1
	s_waitcnt lgkmcnt(14)
	v_mfma_f32_16x16x32_bf16 v[28:31], v[158:161], v[182:185], v[28:31]
	s_waitcnt lgkmcnt(12)
	v_mfma_f32_16x16x32_bf16 v[24:27], v[166:169], v[182:185], v[24:27]
	s_waitcnt lgkmcnt(10)
	v_mfma_f32_16x16x32_bf16 v[20:23], v[170:173], v[182:185], v[20:23]
	s_waitcnt lgkmcnt(8)
	v_mfma_f32_16x16x32_bf16 v[16:19], v[174:177], v[182:185], v[16:19]
	s_setprio 0
	ds_read_b64 v[158:159], v220 offset:1088
	ds_read_b64 v[160:161], v220 offset:1120
	ds_read_b64 v[166:167], v219 offset:1600
	ds_read_b64 v[168:169], v219 offset:1632
	ds_read_b64 v[170:171], v218 offset:1344
	ds_read_b64 v[172:173], v218 offset:1376
	ds_read_b64 v[174:175], v181 offset:1088
	ds_read_b64 v[176:177], v181 offset:1120
	s_setprio 1
	s_waitcnt vmcnt(1) lgkmcnt(15)
	v_mfma_f32_16x16x32_bf16 v[182:185], v[198:201], v[104:107], 0
	s_waitcnt lgkmcnt(13)
	v_mfma_f32_16x16x32_bf16 v[186:189], v[206:209], v[104:107], 0
	s_waitcnt vmcnt(0)
	v_mfma_f32_16x16x32_bf16 v[182:185], v[202:205], v[108:111], v[182:185]
	s_waitcnt lgkmcnt(12)
	v_mfma_f32_16x16x32_bf16 v[186:189], v[210:213], v[108:111], v[186:189]
	s_setprio 0
	s_nop 6
	v_cndmask_b32_e64 v136, v182, v186, s[26:27]
	s_waitcnt lgkmcnt(11)
	v_add_f32_e32 v119, v119, v136
	v_exp_f32_e32 v163, v119
	v_cndmask_b32_e64 v119, v183, v187, s[28:29]
	v_cndmask_b32_e64 v181, v184, v188, s[30:31]
	s_waitcnt lgkmcnt(10)
	v_add_f32_e32 v119, v179, v119
	s_waitcnt lgkmcnt(9)
	v_add_f32_e32 v181, v214, v181
	v_exp_f32_e32 v179, v119
	v_exp_f32_e32 v191, v181
	v_cndmask_b32_e64 v181, v185, v189, s[34:35]
	s_waitcnt lgkmcnt(8)
	v_add_f32_e32 v181, v215, v181
	v_exp_f32_e32 v193, v181
	s_nop 0
	v_cvt_pk_bf16_f32 v243, v163, v179
	v_cvt_pk_bf16_f32 v244, v191, v193
	v_pk_add_f32 v[162:163], v[162:163], 0 op_sel_hi:[1,0]
	v_pk_add_f32 v[162:163], v[178:179], v[162:163]
	v_pk_add_f32 v[162:163], v[190:191], v[162:163]
	v_pk_add_f32 v[162:163], v[192:193], v[162:163]
	v_pk_add_f32 v[124:125], v[124:125], v[162:163]
	v_and_b32_e32 v182, v243, v237
	v_and_b32_e32 v184, v243, v238
	v_and_b32_e32 v183, v244, v239
	v_and_b32_e32 v185, v244, v240
	s_setprio 1
	s_waitcnt lgkmcnt(0)
	v_mfma_f32_16x16x32_bf16 v[12:15], v[174:177], v[182:185], v[12:15]
	v_mfma_f32_16x16x32_bf16 v[8:11], v[170:173], v[182:185], v[8:11]
	v_mfma_f32_16x16x32_bf16 v[4:7], v[166:169], v[182:185], v[4:7]
	v_mfma_f32_16x16x32_bf16 v[0:3], v[158:161], v[182:185], v[0:3]
	s_setprio 0

.LBB0_412:
	s_add_i32 s68, s60, -2
	s_cmp_ge_u32 s68, s38
	s_cselect_b64 s[72:73], -1, 0
	s_cmp_lt_u32 s68, s39
	s_cselect_b64 vcc, -1, 0
	s_and_b64 s[72:73], s[72:73], vcc
	s_andn2_b64 vcc, exec, s[72:73]
	s_cbranch_vccnz .LBB0_414
	v_add_u32_e32 v178, v150, v149
	v_add_u32_e32 v181, 0x6800, v178
	v_add_u32_e32 v218, 0x7000, v178
	v_add_u32_e32 v219, 0x7800, v178
	v_add_u32_e32 v178, v150, v151
	v_add_u32_e32 v119, v148, v149
	v_add_u32_e32 v136, s70, v152
	v_add_u32_sdwa v163, s70, v143 dst_sel:DWORD dst_unused:UNUSED_PAD src0_sel:DWORD src1_sel:BYTE_2
	v_add_u32_sdwa v165, s70, v143 dst_sel:DWORD dst_unused:UNUSED_PAD src0_sel:DWORD src1_sel:BYTE_3
	v_add_u32_e32 v220, 0x6800, v178
	v_add_u32_sdwa v179, s70, v141 dst_sel:DWORD dst_unused:UNUSED_PAD src0_sel:DWORD src1_sel:BYTE_1
	ds_read_b128 v[158:161], v119 offset:18432
	ds_read_b128 v[166:169], v119 offset:18496
	ds_read_b128 v[170:173], v119 offset:20736
	ds_read_b128 v[174:177], v119 offset:20800
	v_add_u32_e32 v162, s70, v153
	ds_read_b64 v[182:183], v181 offset:1024
	ds_read_b64 v[184:185], v181 offset:1056
	ds_read_b64 v[186:187], v218 offset:1280
	ds_read_b64 v[188:189], v218 offset:1312
	ds_read_b64 v[190:191], v219 offset:1536
	ds_read_b64 v[192:193], v219 offset:1568
	ds_read_b64 v[194:195], v220 offset:1024
	ds_read_b64 v[196:197], v220 offset:1056
	ds_read_b128 v[198:201], v119 offset:19584
	ds_read_b128 v[202:205], v119 offset:19648
	ds_read_b128 v[206:209], v119 offset:21888
	ds_read_b128 v[210:213], v119 offset:21952
	v_add_u32_e32 v178, s70, v155
	v_add_u32_sdwa v214, s70, v142 dst_sel:DWORD dst_unused:UNUSED_PAD src0_sel:DWORD src1_sel:BYTE_2
	v_add_u32_sdwa v215, s70, v142 dst_sel:DWORD dst_unused:UNUSED_PAD src0_sel:DWORD src1_sel:BYTE_3
	ds_read_b32 v136, v136 offset:41984
	ds_read_b32 v216, v162 offset:41984
	ds_read_b32 v163, v163 offset:41984
	ds_read_b32 v165, v165 offset:41984
	ds_read_b32 v217, v178 offset:41984
	ds_read_b32 v179, v179 offset:41984
	ds_read_b32 v221, v214 offset:41984
	ds_read_b32 v222, v215 offset:41984
	s_setprio 1
	s_waitcnt vmcnt(7) lgkmcnt(15)
	v_mfma_f32_16x16x32_bf16 v[158:161], v[158:161], v[80:83], 0
	s_waitcnt vmcnt(6)
	v_mfma_f32_16x16x32_bf16 v[158:161], v[166:169], v[84:87], v[158:161]
	v_mfma_f32_16x16x32_bf16 v[166:169], v[170:173], v[80:83], 0
	v_mfma_f32_16x16x32_bf16 v[166:169], v[174:177], v[84:87], v[166:169]
	s_setprio 0
	s_nop 6
	v_cndmask_b32_e64 v158, v166, v158, s[20:21]
	s_waitcnt lgkmcnt(7)
	v_add_f32_e32 v136, v136, v158
	v_exp_f32_e32 v162, v136
	v_cndmask_b32_e64 v136, v159, v167, s[10:11]
	v_cndmask_b32_e64 v159, v160, v168, s[12:13]
	s_waitcnt lgkmcnt(5)
	v_add_f32_e32 v159, v163, v159
	v_add_f32_e32 v136, v216, v136
	v_exp_f32_e32 v214, v159
	v_cndmask_b32_e64 v159, v161, v169, s[14:15]
	v_exp_f32_e32 v178, v136
	s_waitcnt lgkmcnt(4)
	v_add_f32_e32 v159, v165, v159
	v_exp_f32_e32 v216, v159
	s_nop 0
	v_cvt_pk_bf16_f32 v243, v162, v178
	v_cvt_pk_bf16_f32 v244, v214, v216
	v_and_b32_e32 v158, v243, v225
	v_and_b32_e32 v160, v243, v226
	v_and_b32_e32 v159, v244, v227
	v_and_b32_e32 v161, v244, v228
	s_setprio 1
	v_mfma_f32_16x16x32_bf16 v[60:63], v[182:185], v[158:161], v[60:63]
	v_mfma_f32_16x16x32_bf16 v[56:59], v[186:189], v[158:161], v[56:59]
	v_mfma_f32_16x16x32_bf16 v[52:55], v[190:193], v[158:161], v[52:55]
	v_mfma_f32_16x16x32_bf16 v[48:51], v[194:197], v[158:161], v[48:51]
	s_setprio 0
	ds_read_b64 v[158:159], v181 offset:1040
	ds_read_b64 v[160:161], v181 offset:1072
	ds_read_b64 v[166:167], v218 offset:1296
	ds_read_b64 v[168:169], v218 offset:1328
	ds_read_b64 v[170:171], v219 offset:1552
	ds_read_b64 v[172:173], v219 offset:1584
	ds_read_b64 v[174:175], v220 offset:1040
	ds_read_b64 v[176:177], v220 offset:1072
	ds_read_b128 v[182:185], v119 offset:21888
	ds_read_b128 v[186:189], v119 offset:21952
	ds_read_b128 v[190:193], v119 offset:24192
	ds_read_b128 v[194:197], v119 offset:24256
	v_add_u32_e32 v136, s70, v156
	v_add_u32_sdwa v165, s70, v140 dst_sel:DWORD dst_unused:UNUSED_PAD src0_sel:DWORD src1_sel:BYTE_2
	v_add_u32_sdwa v163, s70, v139 dst_sel:DWORD dst_unused:UNUSED_PAD src0_sel:DWORD src1_sel:BYTE_1
	v_add_u32_sdwa v215, s70, v140 dst_sel:DWORD dst_unused:UNUSED_PAD src0_sel:DWORD src1_sel:BYTE_3
	ds_read_b32 v136, v136 offset:41984
	ds_read_b32 v223, v163 offset:41984
	ds_read_b32 v165, v165 offset:41984
	ds_read_b32 v224, v215 offset:41984
	s_setprio 1
	s_waitcnt vmcnt(5)
	v_mfma_f32_16x16x32_bf16 v[198:201], v[198:201], v[88:91], 0
	s_waitcnt vmcnt(4)
	v_mfma_f32_16x16x32_bf16 v[198:201], v[202:205], v[92:95], v[198:201]
	v_mfma_f32_16x16x32_bf16 v[202:205], v[206:209], v[88:91], 0
	v_mfma_f32_16x16x32_bf16 v[202:205], v[210:213], v[92:95], v[202:205]
	s_setprio 0
	s_nop 6
	v_cndmask_b32_e64 v163, v198, v202, s[16:17]
	s_waitcnt lgkmcnt(15)
	v_add_f32_e32 v163, v217, v163
	v_cndmask_b32_e64 v198, v199, v203, s[18:19]
	v_cndmask_b32_e64 v200, v200, v204, s[6:7]
	v_exp_f32_e32 v163, v163
	v_add_f32_e32 v179, v179, v198
	s_waitcnt lgkmcnt(15)
	v_add_f32_e32 v200, v221, v200
	v_exp_f32_e32 v179, v179
	v_exp_f32_e32 v215, v200
	v_cndmask_b32_e64 v200, v201, v205, s[8:9]
	s_waitcnt lgkmcnt(15)
	v_add_f32_e32 v200, v222, v200
	v_exp_f32_e32 v217, v200
	s_nop 0
	v_cvt_pk_bf16_f32 v243, v163, v179
	v_cvt_pk_bf16_f32 v244, v215, v217
	v_pk_add_f32 v[162:163], v[162:163], 0 op_sel_hi:[1,0]
	v_pk_add_f32 v[162:163], v[178:179], v[162:163]
	v_pk_add_f32 v[162:163], v[214:215], v[162:163]
	v_pk_add_f32 v[162:163], v[216:217], v[162:163]
	v_pk_add_f32 v[130:131], v[130:131], v[162:163]
	v_and_b32_e32 v198, v243, v229
	v_and_b32_e32 v200, v243, v230
	v_and_b32_e32 v199, v244, v231
	v_and_b32_e32 v201, v244, v232
	s_setprio 1
	s_waitcnt lgkmcnt(14)
	v_mfma_f32_16x16x32_bf16 v[44:47], v[158:161], v[198:201], v[44:47]
	s_waitcnt lgkmcnt(12)
	v_mfma_f32_16x16x32_bf16 v[40:43], v[166:169], v[198:201], v[40:43]
	s_waitcnt lgkmcnt(10)
	v_mfma_f32_16x16x32_bf16 v[36:39], v[170:173], v[198:201], v[36:39]
	s_waitcnt lgkmcnt(8)
	v_mfma_f32_16x16x32_bf16 v[32:35], v[174:177], v[198:201], v[32:35]
	s_setprio 0
	ds_read_b64 v[158:159], v181 offset:1072
	ds_read_b64 v[160:161], v181 offset:1104
	ds_read_b64 v[166:167], v218 offset:1328
	ds_read_b64 v[168:169], v218 offset:1360
	ds_read_b64 v[170:171], v219 offset:1584
	ds_read_b64 v[172:173], v219 offset:1616
	ds_read_b64 v[174:175], v220 offset:1072
	ds_read_b64 v[176:177], v220 offset:1104
	ds_read_b128 v[198:201], v119 offset:23040
	ds_read_b128 v[202:205], v119 offset:23104
	v_add_u32_e32 v119, v148, v151
	ds_read_b128 v[206:209], v119 offset:18432
	ds_read_b128 v[210:213], v119 offset:18496
	v_add_u32_e32 v119, s70, v154
	v_add_u32_sdwa v162, s70, v144 dst_sel:DWORD dst_unused:UNUSED_PAD src0_sel:DWORD src1_sel:BYTE_1
	v_add_u32_sdwa v163, s70, v145 dst_sel:DWORD dst_unused:UNUSED_PAD src0_sel:DWORD src1_sel:BYTE_2
	v_add_u32_sdwa v178, s70, v145 dst_sel:DWORD dst_unused:UNUSED_PAD src0_sel:DWORD src1_sel:BYTE_3
	ds_read_b32 v119, v119 offset:41984
	ds_read_b32 v179, v162 offset:41984
	ds_read_b32 v214, v163 offset:41984
	ds_read_b32 v215, v178 offset:41984
	s_setprio 1
	s_waitcnt vmcnt(3) lgkmcnt(15)
	v_mfma_f32_16x16x32_bf16 v[182:185], v[182:185], v[96:99], 0
	s_waitcnt vmcnt(2)
	v_mfma_f32_16x16x32_bf16 v[182:185], v[186:189], v[100:103], v[182:185]
	v_mfma_f32_16x16x32_bf16 v[186:189], v[190:193], v[96:99], 0
	v_mfma_f32_16x16x32_bf16 v[186:189], v[194:197], v[100:103], v[186:189]
	s_setprio 0
	s_nop 6
	v_cndmask_b32_e64 v162, v186, v182, s[2:3]
	v_add_f32_e32 v136, v136, v162
	v_exp_f32_e32 v162, v136
	v_cndmask_b32_e64 v136, v187, v183, s[4:5]
	v_cndmask_b32_e64 v183, v184, v188, s[22:23]
	s_waitcnt lgkmcnt(15)
	v_add_f32_e32 v165, v165, v183
	v_exp_f32_e32 v190, v165
	v_cndmask_b32_e64 v165, v185, v189, s[24:25]
	v_add_f32_e32 v136, v223, v136
	s_waitcnt lgkmcnt(15)
	v_add_f32_e32 v165, v224, v165
	v_exp_f32_e32 v178, v136
	v_exp_f32_e32 v192, v165
	s_nop 0
	v_cvt_pk_bf16_f32 v243, v162, v178
	v_cvt_pk_bf16_f32 v244, v190, v192
	v_and_b32_e32 v182, v243, v233
	v_and_b32_e32 v184, v243, v234
	v_and_b32_e32 v183, v244, v235
	v_and_b32_e32 v185, v244, v236
	s_setprio 1
	s_waitcnt lgkmcnt(14)
	v_mfma_f32_16x16x32_bf16 v[28:31], v[158:161], v[182:185], v[28:31]
	s_waitcnt lgkmcnt(12)
	v_mfma_f32_16x16x32_bf16 v[24:27], v[166:169], v[182:185], v[24:27]
	s_waitcnt lgkmcnt(10)
	v_mfma_f32_16x16x32_bf16 v[20:23], v[170:173], v[182:185], v[20:23]
	s_waitcnt lgkmcnt(8)
	v_mfma_f32_16x16x32_bf16 v[16:19], v[174:177], v[182:185], v[16:19]
	s_setprio 0
	ds_read_b64 v[158:159], v220 offset:1088
	ds_read_b64 v[160:161], v220 offset:1120
	ds_read_b64 v[166:167], v219 offset:1600
	ds_read_b64 v[168:169], v219 offset:1632
	ds_read_b64 v[170:171], v218 offset:1344
	ds_read_b64 v[172:173], v218 offset:1376
	ds_read_b64 v[174:175], v181 offset:1088
	ds_read_b64 v[176:177], v181 offset:1120
	s_setprio 1
	s_waitcnt vmcnt(1) lgkmcnt(15)
	v_mfma_f32_16x16x32_bf16 v[182:185], v[198:201], v[104:107], 0
	s_waitcnt lgkmcnt(13)
	v_mfma_f32_16x16x32_bf16 v[186:189], v[206:209], v[104:107], 0
	s_waitcnt vmcnt(0)
	v_mfma_f32_16x16x32_bf16 v[182:185], v[202:205], v[108:111], v[182:185]
	s_waitcnt lgkmcnt(12)
	v_mfma_f32_16x16x32_bf16 v[186:189], v[210:213], v[108:111], v[186:189]
	s_setprio 0
	s_nop 6
	v_cndmask_b32_e64 v136, v182, v186, s[26:27]
	s_waitcnt lgkmcnt(11)
	v_add_f32_e32 v119, v119, v136
	v_exp_f32_e32 v163, v119
	v_cndmask_b32_e64 v119, v183, v187, s[28:29]
	v_cndmask_b32_e64 v181, v184, v188, s[30:31]
	s_waitcnt lgkmcnt(10)
	v_add_f32_e32 v119, v179, v119
	s_waitcnt lgkmcnt(9)
	v_add_f32_e32 v181, v214, v181
	v_exp_f32_e32 v179, v119
	v_exp_f32_e32 v191, v181
	v_cndmask_b32_e64 v181, v185, v189, s[34:35]
	s_waitcnt lgkmcnt(8)
	v_add_f32_e32 v181, v215, v181
	v_exp_f32_e32 v193, v181
	s_nop 0
	v_cvt_pk_bf16_f32 v243, v163, v179
	v_cvt_pk_bf16_f32 v244, v191, v193
	v_pk_add_f32 v[162:163], v[162:163], 0 op_sel_hi:[1,0]
	v_pk_add_f32 v[162:163], v[178:179], v[162:163]
	v_pk_add_f32 v[162:163], v[190:191], v[162:163]
	v_pk_add_f32 v[162:163], v[192:193], v[162:163]
	v_pk_add_f32 v[124:125], v[124:125], v[162:163]
	v_and_b32_e32 v182, v243, v237
	v_and_b32_e32 v184, v243, v238
	v_and_b32_e32 v183, v244, v239
	v_and_b32_e32 v185, v244, v240
	s_setprio 1
	s_waitcnt lgkmcnt(0)
	v_mfma_f32_16x16x32_bf16 v[12:15], v[174:177], v[182:185], v[12:15]
	v_mfma_f32_16x16x32_bf16 v[8:11], v[170:173], v[182:185], v[8:11]
	v_mfma_f32_16x16x32_bf16 v[4:7], v[166:169], v[182:185], v[4:7]
	v_mfma_f32_16x16x32_bf16 v[0:3], v[158:161], v[182:185], v[0:3]
	s_setprio 0

.LBB0_483:
	s_add_i32 s94, s38, s92
	s_lshl_b32 s38, s94, 6
	s_add_i32 s38, s38, s39
	v_add_u32_e32 v128, s38, v146
	s_lshl_b32 s38, s67, 1
	s_mov_b32 s39, s49
	v_ashrrev_i32_e32 v129, 31, v128
	v_lshl_add_u64 v[0:1], v[116:117], 0, s[38:39]
	v_lshlrev_b64 v[2:3], 10, v[128:129]
	v_add_u32_e32 v126, 16, v128
	v_lshl_add_u64 v[2:3], v[0:1], 0, v[2:3]
	v_ashrrev_i32_e32 v127, 31, v126
	global_load_dwordx4 v[80:83], v[2:3], off
	global_load_dwordx4 v[84:87], v[2:3], off offset:64
	v_lshlrev_b64 v[2:3], 10, v[126:127]
	v_add_u32_e32 v122, 32, v128
	v_lshl_add_u64 v[2:3], v[0:1], 0, v[2:3]
	v_ashrrev_i32_e32 v123, 31, v122
	global_load_dwordx4 v[88:91], v[2:3], off
	global_load_dwordx4 v[92:95], v[2:3], off offset:64
	v_lshlrev_b64 v[2:3], 10, v[122:123]
	v_add_u32_e32 v120, 48, v128
	v_lshl_add_u64 v[2:3], v[0:1], 0, v[2:3]
	v_ashrrev_i32_e32 v121, 31, v120
	global_load_dwordx4 v[96:99], v[2:3], off
	global_load_dwordx4 v[100:103], v[2:3], off offset:64
	v_lshlrev_b64 v[2:3], 10, v[120:121]
	v_lshl_add_u64 v[0:1], v[0:1], 0, v[2:3]
	global_load_dwordx4 v[104:107], v[0:1], off
	global_load_dwordx4 v[108:111], v[0:1], off offset:64
	v_mov_b32_e32 v131, 0
	s_andn2_b64 vcc, exec, s[68:69]
	v_mov_b32_e32 v130, 0
	v_mov_b32_e32 v125, 0
	v_mov_b32_e32 v124, 0
	v_mov_b32_e32 v63, 0
	v_mov_b32_e32 v62, 0
	v_mov_b32_e32 v61, 0
	v_mov_b32_e32 v60, 0
	v_mov_b32_e32 v59, 0
	v_mov_b32_e32 v58, 0
	v_mov_b32_e32 v57, 0
	v_mov_b32_e32 v56, 0
	v_mov_b32_e32 v55, 0
	v_mov_b32_e32 v54, 0
	v_mov_b32_e32 v53, 0
	v_mov_b32_e32 v52, 0
	v_mov_b32_e32 v51, 0
	v_mov_b32_e32 v50, 0
	v_mov_b32_e32 v49, 0
	v_mov_b32_e32 v48, 0
	v_mov_b32_e32 v47, 0
	v_mov_b32_e32 v46, 0
	v_mov_b32_e32 v45, 0
	v_mov_b32_e32 v44, 0
	v_mov_b32_e32 v43, 0
	v_mov_b32_e32 v42, 0
	v_mov_b32_e32 v41, 0
	v_mov_b32_e32 v40, 0
	v_mov_b32_e32 v39, 0
	v_mov_b32_e32 v38, 0
	v_mov_b32_e32 v37, 0
	v_mov_b32_e32 v36, 0
	v_mov_b32_e32 v35, 0
	v_mov_b32_e32 v34, 0
	v_mov_b32_e32 v33, 0
	v_mov_b32_e32 v32, 0
	v_mov_b32_e32 v31, 0
	v_mov_b32_e32 v30, 0
	v_mov_b32_e32 v29, 0
	v_mov_b32_e32 v28, 0
	v_mov_b32_e32 v27, 0
	v_mov_b32_e32 v26, 0
	v_mov_b32_e32 v25, 0
	v_mov_b32_e32 v24, 0
	v_mov_b32_e32 v23, 0
	v_mov_b32_e32 v22, 0
	v_mov_b32_e32 v21, 0
	v_mov_b32_e32 v20, 0
	v_mov_b32_e32 v19, 0
	v_mov_b32_e32 v18, 0
	v_mov_b32_e32 v17, 0
	v_mov_b32_e32 v16, 0
	v_mov_b32_e32 v15, 0
	v_mov_b32_e32 v14, 0
	v_mov_b32_e32 v13, 0
	v_mov_b32_e32 v12, 0
	v_mov_b32_e32 v11, 0
	v_mov_b32_e32 v10, 0
	v_mov_b32_e32 v9, 0
	v_mov_b32_e32 v8, 0
	v_mov_b32_e32 v7, 0
	v_mov_b32_e32 v6, 0
	v_mov_b32_e32 v5, 0
	v_mov_b32_e32 v4, 0
	v_mov_b32_e32 v3, 0
	v_mov_b32_e32 v2, 0
	v_mov_b32_e32 v1, 0
	v_mov_b32_e32 v0, 0
	v_mov_b32_e32 v241, 0xffff
	v_mov_b32_e32 v242, 0xffff0000
	v_cndmask_b32_e64 v243, 0, v241, s[20:21]
	v_cndmask_b32_e64 v244, v242, 0, s[10:11]
	v_or_b32_e32 v225, v243, v244
	v_cndmask_b32_e64 v243, v241, 0, s[20:21]
	v_cndmask_b32_e64 v244, 0, v242, s[10:11]
	v_or_b32_e32 v226, v243, v244
	v_cndmask_b32_e64 v243, v241, 0, s[12:13]
	v_cndmask_b32_e64 v244, v242, 0, s[14:15]
	v_or_b32_e32 v227, v243, v244
	v_cndmask_b32_e64 v243, 0, v241, s[12:13]
	v_cndmask_b32_e64 v244, 0, v242, s[14:15]
	v_or_b32_e32 v228, v243, v244
	v_cndmask_b32_e64 v243, v241, 0, s[16:17]
	v_cndmask_b32_e64 v244, v242, 0, s[18:19]
	v_or_b32_e32 v229, v243, v244
	v_cndmask_b32_e64 v243, 0, v241, s[16:17]
	v_cndmask_b32_e64 v244, 0, v242, s[18:19]
	v_or_b32_e32 v230, v243, v244
	v_cndmask_b32_e64 v243, v241, 0, s[6:7]
	v_cndmask_b32_e64 v244, v242, 0, s[8:9]
	v_or_b32_e32 v231, v243, v244
	v_cndmask_b32_e64 v243, 0, v241, s[6:7]
	v_cndmask_b32_e64 v244, 0, v242, s[8:9]
	v_or_b32_e32 v232, v243, v244
	v_cndmask_b32_e64 v243, 0, v241, s[2:3]
	v_cndmask_b32_e64 v244, 0, v242, s[4:5]
	v_or_b32_e32 v233, v243, v244
	v_cndmask_b32_e64 v243, v241, 0, s[2:3]
	v_cndmask_b32_e64 v244, v242, 0, s[4:5]
	v_or_b32_e32 v234, v243, v244
	v_cndmask_b32_e64 v243, v241, 0, s[22:23]
	v_cndmask_b32_e64 v244, v242, 0, s[24:25]
	v_or_b32_e32 v235, v243, v244
	v_cndmask_b32_e64 v243, 0, v241, s[22:23]
	v_cndmask_b32_e64 v244, 0, v242, s[24:25]
	v_or_b32_e32 v236, v243, v244
	v_cndmask_b32_e64 v243, v241, 0, s[26:27]
	v_cndmask_b32_e64 v244, v242, 0, s[28:29]
	v_or_b32_e32 v237, v243, v244
	v_cndmask_b32_e64 v243, 0, v241, s[26:27]
	v_cndmask_b32_e64 v244, 0, v242, s[28:29]
	v_or_b32_e32 v238, v243, v244
	v_cndmask_b32_e64 v243, v241, 0, s[30:31]
	v_cndmask_b32_e64 v244, v242, 0, s[34:35]
	v_or_b32_e32 v239, v243, v244
	v_cndmask_b32_e64 v243, 0, v241, s[30:31]
	v_cndmask_b32_e64 v244, 0, v242, s[34:35]
	v_or_b32_e32 v240, v243, v244
	s_waitcnt vmcnt(9)
	ds_write_b128 v157, v[64:67]
	s_waitcnt vmcnt(8)
	ds_write_b128 v157, v[68:71] offset:9216
	s_waitcnt lgkmcnt(0)
	s_barrier
	s_cbranch_vccnz .LBB0_500
	s_max_i32 s38, s94, 4
	s_add_i32 s38, s38, -4
	s_min_u32 s38, s38, s66
	s_mov_b32 s67, s49
	v_mov_b32_e32 v133, v113
	s_add_i32 s39, s38, 8
	v_mov_b32_e32 v0, s66
	v_cmp_lt_u64_e32 vcc, s[66:67], v[132:133]
	s_add_u32 s66, s80, s48
	v_mov_b32_e32 v1, v113
	v_cndmask_b32_e32 v2, v132, v0, vcc
	v_lshlrev_b32_e32 v0, 16, v2
	s_addc_u32 s67, s81, 0
	v_lshl_add_u64 v[0:1], s[66:67], 0, v[0:1]
	v_lshl_add_u64 v[132:133], v[0:1], 0, v[134:135]
	v_lshlrev_b32_e32 v0, 7, v2
	v_mov_b32_e32 v1, v113
	s_mul_i32 s68, s77, 0x780
	v_lshlrev_b32_e32 v2, 1, v136
	v_mov_b32_e32 v3, v113
	v_lshl_add_u64 v[0:1], s[64:65], 0, v[0:1]
	s_lshl_b32 s64, s89, 7
	v_lshl_add_u64 v[134:135], v[0:1], 0, v[2:3]
	s_add_i32 s68, s68, s64
	s_lshl_b32 s64, s94, 7
	v_mov_b32_e32 v2, v113
	s_sub_i32 s64, s68, s64
	v_mov_b32_e32 v124, v113
	v_mov_b32_e32 v125, v113
	v_mov_b32_e32 v0, v113
	v_mov_b32_e32 v1, v113
	v_mov_b64_e32 v[6:7], v[2:3]
	v_mov_b64_e32 v[10:11], v[2:3]
	v_mov_b64_e32 v[14:15], v[2:3]
	v_mov_b64_e32 v[18:19], v[2:3]
	v_mov_b64_e32 v[22:23], v[2:3]
	v_mov_b64_e32 v[26:27], v[2:3]
	v_mov_b64_e32 v[30:31], v[2:3]
	v_mov_b64_e32 v[34:35], v[2:3]
	v_mov_b64_e32 v[38:39], v[2:3]
	v_mov_b64_e32 v[42:43], v[2:3]
	v_mov_b64_e32 v[46:47], v[2:3]
	v_mov_b64_e32 v[50:51], v[2:3]
	v_mov_b64_e32 v[54:55], v[2:3]
	v_mov_b64_e32 v[58:59], v[2:3]
	v_mov_b64_e32 v[62:63], v[2:3]
	s_add_i32 s48, s89, 3
	s_add_i32 s66, s64, 0
	v_mov_b64_e32 v[4:5], v[0:1]
	v_mov_b64_e32 v[8:9], v[0:1]
	v_mov_b64_e32 v[12:13], v[0:1]
	v_mov_b64_e32 v[16:17], v[0:1]
	v_mov_b64_e32 v[20:21], v[0:1]
	v_mov_b64_e32 v[24:25], v[0:1]
	v_mov_b64_e32 v[28:29], v[0:1]
	v_mov_b64_e32 v[32:33], v[0:1]
	v_mov_b64_e32 v[36:37], v[0:1]
	v_mov_b64_e32 v[40:41], v[0:1]
	v_mov_b64_e32 v[44:45], v[0:1]
	v_mov_b64_e32 v[48:49], v[0:1]
	v_mov_b64_e32 v[52:53], v[0:1]
	v_mov_b64_e32 v[56:57], v[0:1]
	v_mov_b64_e32 v[60:61], v[0:1]
	v_mov_b64_e32 v[130:131], v[124:125]
	s_branch .LBB0_487

.LBB0_489:
	s_add_i32 s68, s48, -3
	s_cmp_ge_u32 s68, s38
	s_cselect_b64 s[64:65], -1, 0
	s_cmp_lt_u32 s68, s39
	s_cselect_b64 s[94:95], -1, 0
	s_and_b64 s[64:65], s[64:65], s[94:95]
	s_andn2_b64 vcc, exec, s[64:65]
	s_cbranch_vccnz .LBB0_491
	v_add_u32_e32 v178, v150, v149
	v_add_u32_e32 v181, 0x2000, v178
	v_add_u32_e32 v218, 0x2800, v178
	v_add_u32_e32 v219, 0x3000, v178
	v_add_u32_e32 v178, v150, v151
	v_add_u32_e32 v119, v148, v149
	v_add_u32_e32 v136, s66, v152
	v_add_u32_sdwa v163, s66, v143 dst_sel:DWORD dst_unused:UNUSED_PAD src0_sel:DWORD src1_sel:BYTE_2
	v_add_u32_sdwa v165, s66, v143 dst_sel:DWORD dst_unused:UNUSED_PAD src0_sel:DWORD src1_sel:BYTE_3
	v_add_u32_e32 v220, 0x2000, v178
	v_add_u32_sdwa v179, s66, v141 dst_sel:DWORD dst_unused:UNUSED_PAD src0_sel:DWORD src1_sel:BYTE_1
	ds_read_b128 v[158:161], v119
	ds_read_b128 v[166:169], v119 offset:64
	ds_read_b128 v[170:173], v119 offset:2304
	ds_read_b128 v[174:177], v119 offset:2368
	v_add_u32_e32 v162, s66, v153
	ds_read_b64 v[182:183], v181 offset:1024
	ds_read_b64 v[184:185], v181 offset:1056
	ds_read_b64 v[186:187], v218 offset:1280
	ds_read_b64 v[188:189], v218 offset:1312
	ds_read_b64 v[190:191], v219 offset:1536
	ds_read_b64 v[192:193], v219 offset:1568
	ds_read_b64 v[194:195], v220 offset:1024
	ds_read_b64 v[196:197], v220 offset:1056
	ds_read_b128 v[198:201], v119 offset:1152
	ds_read_b128 v[202:205], v119 offset:1216
	ds_read_b128 v[206:209], v119 offset:3456
	ds_read_b128 v[210:213], v119 offset:3520
	v_add_u32_e32 v178, s66, v155
	v_add_u32_sdwa v214, s66, v142 dst_sel:DWORD dst_unused:UNUSED_PAD src0_sel:DWORD src1_sel:BYTE_2
	v_add_u32_sdwa v215, s66, v142 dst_sel:DWORD dst_unused:UNUSED_PAD src0_sel:DWORD src1_sel:BYTE_3
	ds_read_b32 v136, v136 offset:41856
	ds_read_b32 v216, v162 offset:41856
	ds_read_b32 v163, v163 offset:41856
	ds_read_b32 v165, v165 offset:41856
	ds_read_b32 v217, v178 offset:41856
	ds_read_b32 v179, v179 offset:41856
	ds_read_b32 v221, v214 offset:41856
	ds_read_b32 v222, v215 offset:41856
	s_setprio 1
	s_waitcnt vmcnt(7) lgkmcnt(15)
	v_mfma_f32_16x16x32_bf16 v[158:161], v[158:161], v[80:83], 0
	s_waitcnt vmcnt(6)
	v_mfma_f32_16x16x32_bf16 v[158:161], v[166:169], v[84:87], v[158:161]
	v_mfma_f32_16x16x32_bf16 v[166:169], v[170:173], v[80:83], 0
	v_mfma_f32_16x16x32_bf16 v[166:169], v[174:177], v[84:87], v[166:169]
	s_setprio 0
	s_nop 6
	v_cndmask_b32_e64 v158, v166, v158, s[20:21]
	s_waitcnt lgkmcnt(7)
	v_add_f32_e32 v136, v136, v158
	v_exp_f32_e32 v162, v136
	v_cndmask_b32_e64 v136, v159, v167, s[10:11]
	v_cndmask_b32_e64 v159, v160, v168, s[12:13]
	s_waitcnt lgkmcnt(5)
	v_add_f32_e32 v159, v163, v159
	v_add_f32_e32 v136, v216, v136
	v_exp_f32_e32 v214, v159
	v_cndmask_b32_e64 v159, v161, v169, s[14:15]
	v_exp_f32_e32 v178, v136
	s_waitcnt lgkmcnt(4)
	v_add_f32_e32 v159, v165, v159
	v_exp_f32_e32 v216, v159
	s_nop 0
	v_cvt_pk_bf16_f32 v243, v162, v178
	v_cvt_pk_bf16_f32 v244, v214, v216
	v_and_b32_e32 v158, v243, v225
	v_and_b32_e32 v160, v243, v226
	v_and_b32_e32 v159, v244, v227
	v_and_b32_e32 v161, v244, v228
	s_setprio 1
	v_mfma_f32_16x16x32_bf16 v[60:63], v[182:185], v[158:161], v[60:63]
	v_mfma_f32_16x16x32_bf16 v[56:59], v[186:189], v[158:161], v[56:59]
	v_mfma_f32_16x16x32_bf16 v[52:55], v[190:193], v[158:161], v[52:55]
	v_mfma_f32_16x16x32_bf16 v[48:51], v[194:197], v[158:161], v[48:51]
	s_setprio 0
	ds_read_b64 v[158:159], v181 offset:1040
	ds_read_b64 v[160:161], v181 offset:1072
	ds_read_b64 v[166:167], v218 offset:1296
	ds_read_b64 v[168:169], v218 offset:1328
	ds_read_b64 v[170:171], v219 offset:1552
	ds_read_b64 v[172:173], v219 offset:1584
	ds_read_b64 v[174:175], v220 offset:1040
	ds_read_b64 v[176:177], v220 offset:1072
	ds_read_b128 v[182:185], v119 offset:3456
	ds_read_b128 v[186:189], v119 offset:3520
	ds_read_b128 v[190:193], v119 offset:5760
	ds_read_b128 v[194:197], v119 offset:5824
	v_add_u32_e32 v136, s66, v156
	v_add_u32_sdwa v165, s66, v140 dst_sel:DWORD dst_unused:UNUSED_PAD src0_sel:DWORD src1_sel:BYTE_2
	v_add_u32_sdwa v163, s66, v139 dst_sel:DWORD dst_unused:UNUSED_PAD src0_sel:DWORD src1_sel:BYTE_1
	v_add_u32_sdwa v215, s66, v140 dst_sel:DWORD dst_unused:UNUSED_PAD src0_sel:DWORD src1_sel:BYTE_3
	ds_read_b32 v136, v136 offset:41856
	ds_read_b32 v223, v163 offset:41856
	ds_read_b32 v165, v165 offset:41856
	ds_read_b32 v224, v215 offset:41856
	s_setprio 1
	s_waitcnt vmcnt(5)
	v_mfma_f32_16x16x32_bf16 v[198:201], v[198:201], v[88:91], 0
	s_waitcnt vmcnt(4)
	v_mfma_f32_16x16x32_bf16 v[198:201], v[202:205], v[92:95], v[198:201]
	v_mfma_f32_16x16x32_bf16 v[202:205], v[206:209], v[88:91], 0
	v_mfma_f32_16x16x32_bf16 v[202:205], v[210:213], v[92:95], v[202:205]
	s_setprio 0
	s_nop 6
	v_cndmask_b32_e64 v163, v198, v202, s[16:17]
	s_waitcnt lgkmcnt(15)
	v_add_f32_e32 v163, v217, v163
	v_cndmask_b32_e64 v198, v199, v203, s[18:19]
	v_cndmask_b32_e64 v200, v200, v204, s[6:7]
	v_exp_f32_e32 v163, v163
	v_add_f32_e32 v179, v179, v198
	s_waitcnt lgkmcnt(15)
	v_add_f32_e32 v200, v221, v200
	v_exp_f32_e32 v179, v179
	v_exp_f32_e32 v215, v200
	v_cndmask_b32_e64 v200, v201, v205, s[8:9]
	s_waitcnt lgkmcnt(15)
	v_add_f32_e32 v200, v222, v200
	v_exp_f32_e32 v217, v200
	s_nop 0
	v_cvt_pk_bf16_f32 v243, v163, v179
	v_cvt_pk_bf16_f32 v244, v215, v217
	v_pk_add_f32 v[162:163], v[162:163], 0 op_sel_hi:[1,0]
	v_pk_add_f32 v[162:163], v[178:179], v[162:163]
	v_pk_add_f32 v[162:163], v[214:215], v[162:163]
	v_pk_add_f32 v[162:163], v[216:217], v[162:163]
	v_pk_add_f32 v[130:131], v[130:131], v[162:163]
	v_and_b32_e32 v198, v243, v229
	v_and_b32_e32 v200, v243, v230
	v_and_b32_e32 v199, v244, v231
	v_and_b32_e32 v201, v244, v232
	s_setprio 1
	s_waitcnt lgkmcnt(14)
	v_mfma_f32_16x16x32_bf16 v[44:47], v[158:161], v[198:201], v[44:47]
	s_waitcnt lgkmcnt(12)
	v_mfma_f32_16x16x32_bf16 v[40:43], v[166:169], v[198:201], v[40:43]
	s_waitcnt lgkmcnt(10)
	v_mfma_f32_16x16x32_bf16 v[36:39], v[170:173], v[198:201], v[36:39]
	s_waitcnt lgkmcnt(8)
	v_mfma_f32_16x16x32_bf16 v[32:35], v[174:177], v[198:201], v[32:35]
	s_setprio 0
	ds_read_b64 v[158:159], v181 offset:1072
	ds_read_b64 v[160:161], v181 offset:1104
	ds_read_b64 v[166:167], v218 offset:1328
	ds_read_b64 v[168:169], v218 offset:1360
	ds_read_b64 v[170:171], v219 offset:1584
	ds_read_b64 v[172:173], v219 offset:1616
	ds_read_b64 v[174:175], v220 offset:1072
	ds_read_b64 v[176:177], v220 offset:1104
	ds_read_b128 v[198:201], v119 offset:4608
	ds_read_b128 v[202:205], v119 offset:4672
	v_add_u32_e32 v119, v148, v151
	ds_read_b128 v[206:209], v119
	ds_read_b128 v[210:213], v119 offset:64
	v_add_u32_e32 v119, s66, v154
	v_add_u32_sdwa v162, s66, v144 dst_sel:DWORD dst_unused:UNUSED_PAD src0_sel:DWORD src1_sel:BYTE_1
	v_add_u32_sdwa v163, s66, v145 dst_sel:DWORD dst_unused:UNUSED_PAD src0_sel:DWORD src1_sel:BYTE_2
	v_add_u32_sdwa v178, s66, v145 dst_sel:DWORD dst_unused:UNUSED_PAD src0_sel:DWORD src1_sel:BYTE_3
	ds_read_b32 v119, v119 offset:41856
	ds_read_b32 v179, v162 offset:41856
	ds_read_b32 v214, v163 offset:41856
	ds_read_b32 v215, v178 offset:41856
	s_setprio 1
	s_waitcnt vmcnt(3) lgkmcnt(15)
	v_mfma_f32_16x16x32_bf16 v[182:185], v[182:185], v[96:99], 0
	s_waitcnt vmcnt(2)
	v_mfma_f32_16x16x32_bf16 v[182:185], v[186:189], v[100:103], v[182:185]
	v_mfma_f32_16x16x32_bf16 v[186:189], v[190:193], v[96:99], 0
	v_mfma_f32_16x16x32_bf16 v[186:189], v[194:197], v[100:103], v[186:189]
	s_setprio 0
	s_nop 6
	v_cndmask_b32_e64 v162, v186, v182, s[2:3]
	v_add_f32_e32 v136, v136, v162
	v_exp_f32_e32 v162, v136
	v_cndmask_b32_e64 v136, v187, v183, s[4:5]
	v_cndmask_b32_e64 v183, v184, v188, s[22:23]
	s_waitcnt lgkmcnt(15)
	v_add_f32_e32 v165, v165, v183
	v_exp_f32_e32 v190, v165
	v_cndmask_b32_e64 v165, v185, v189, s[24:25]
	v_add_f32_e32 v136, v223, v136
	s_waitcnt lgkmcnt(15)
	v_add_f32_e32 v165, v224, v165
	v_exp_f32_e32 v178, v136
	v_exp_f32_e32 v192, v165
	s_nop 0
	v_cvt_pk_bf16_f32 v243, v162, v178
	v_cvt_pk_bf16_f32 v244, v190, v192
	v_and_b32_e32 v182, v243, v233
	v_and_b32_e32 v184, v243, v234
	v_and_b32_e32 v183, v244, v235
	v_and_b32_e32 v185, v244, v236
	s_setprio 1
	s_waitcnt lgkmcnt(14)
	v_mfma_f32_16x16x32_bf16 v[28:31], v[158:161], v[182:185], v[28:31]
	s_waitcnt lgkmcnt(12)
	v_mfma_f32_16x16x32_bf16 v[24:27], v[166:169], v[182:185], v[24:27]
	s_waitcnt lgkmcnt(10)
	v_mfma_f32_16x16x32_bf16 v[20:23], v[170:173], v[182:185], v[20:23]
	s_waitcnt lgkmcnt(8)
	v_mfma_f32_16x16x32_bf16 v[16:19], v[174:177], v[182:185], v[16:19]
	s_setprio 0
	ds_read_b64 v[158:159], v220 offset:1088
	ds_read_b64 v[160:161], v220 offset:1120
	ds_read_b64 v[166:167], v219 offset:1600
	ds_read_b64 v[168:169], v219 offset:1632
	ds_read_b64 v[170:171], v218 offset:1344
	ds_read_b64 v[172:173], v218 offset:1376
	ds_read_b64 v[174:175], v181 offset:1088
	ds_read_b64 v[176:177], v181 offset:1120
	s_setprio 1
	s_waitcnt vmcnt(1) lgkmcnt(15)
	v_mfma_f32_16x16x32_bf16 v[182:185], v[198:201], v[104:107], 0
	s_waitcnt lgkmcnt(13)
	v_mfma_f32_16x16x32_bf16 v[186:189], v[206:209], v[104:107], 0
	s_waitcnt vmcnt(0)
	v_mfma_f32_16x16x32_bf16 v[182:185], v[202:205], v[108:111], v[182:185]
	s_waitcnt lgkmcnt(12)
	v_mfma_f32_16x16x32_bf16 v[186:189], v[210:213], v[108:111], v[186:189]
	s_setprio 0
	s_nop 6
	v_cndmask_b32_e64 v136, v182, v186, s[26:27]
	s_waitcnt lgkmcnt(11)
	v_add_f32_e32 v119, v119, v136
	v_exp_f32_e32 v163, v119
	v_cndmask_b32_e64 v119, v183, v187, s[28:29]
	v_cndmask_b32_e64 v181, v184, v188, s[30:31]
	s_waitcnt lgkmcnt(10)
	v_add_f32_e32 v119, v179, v119
	s_waitcnt lgkmcnt(9)
	v_add_f32_e32 v181, v214, v181
	v_exp_f32_e32 v179, v119
	v_exp_f32_e32 v191, v181
	v_cndmask_b32_e64 v181, v185, v189, s[34:35]
	s_waitcnt lgkmcnt(8)
	v_add_f32_e32 v181, v215, v181
	v_exp_f32_e32 v193, v181
	s_nop 0
	v_cvt_pk_bf16_f32 v243, v163, v179
	v_cvt_pk_bf16_f32 v244, v191, v193
	v_pk_add_f32 v[162:163], v[162:163], 0 op_sel_hi:[1,0]
	v_pk_add_f32 v[162:163], v[178:179], v[162:163]
	v_pk_add_f32 v[162:163], v[190:191], v[162:163]
	v_pk_add_f32 v[162:163], v[192:193], v[162:163]
	v_pk_add_f32 v[124:125], v[124:125], v[162:163]
	v_and_b32_e32 v182, v243, v237
	v_and_b32_e32 v184, v243, v238
	v_and_b32_e32 v183, v244, v239
	v_and_b32_e32 v185, v244, v240
	s_setprio 1
	s_waitcnt lgkmcnt(0)
	v_mfma_f32_16x16x32_bf16 v[12:15], v[174:177], v[182:185], v[12:15]
	v_mfma_f32_16x16x32_bf16 v[8:11], v[170:173], v[182:185], v[8:11]
	v_mfma_f32_16x16x32_bf16 v[4:7], v[166:169], v[182:185], v[4:7]
	v_mfma_f32_16x16x32_bf16 v[0:3], v[158:161], v[182:185], v[0:3]
	s_setprio 0

.LBB0_496:
	s_add_i32 s64, s48, -2
	s_cmp_ge_u32 s64, s38
	s_cselect_b64 s[68:69], -1, 0
	s_cmp_lt_u32 s64, s39
	s_cselect_b64 s[94:95], -1, 0
	s_and_b64 s[68:69], s[68:69], s[94:95]
	s_andn2_b64 vcc, exec, s[68:69]
	s_cbranch_vccnz .LBB0_498
	v_add_u32_e32 v178, v150, v149
	v_add_u32_e32 v181, 0x6800, v178
	v_add_u32_e32 v218, 0x7000, v178
	v_add_u32_e32 v219, 0x7800, v178
	v_add_u32_e32 v178, v150, v151
	v_add_u32_e32 v119, v148, v149
	v_add_u32_e32 v136, s66, v152
	v_add_u32_sdwa v163, s66, v143 dst_sel:DWORD dst_unused:UNUSED_PAD src0_sel:DWORD src1_sel:BYTE_2
	v_add_u32_sdwa v165, s66, v143 dst_sel:DWORD dst_unused:UNUSED_PAD src0_sel:DWORD src1_sel:BYTE_3
	v_add_u32_e32 v220, 0x6800, v178
	v_add_u32_sdwa v179, s66, v141 dst_sel:DWORD dst_unused:UNUSED_PAD src0_sel:DWORD src1_sel:BYTE_1
	ds_read_b128 v[158:161], v119 offset:18432
	ds_read_b128 v[166:169], v119 offset:18496
	ds_read_b128 v[170:173], v119 offset:20736
	ds_read_b128 v[174:177], v119 offset:20800
	v_add_u32_e32 v162, s66, v153
	ds_read_b64 v[182:183], v181 offset:1024
	ds_read_b64 v[184:185], v181 offset:1056
	ds_read_b64 v[186:187], v218 offset:1280
	ds_read_b64 v[188:189], v218 offset:1312
	ds_read_b64 v[190:191], v219 offset:1536
	ds_read_b64 v[192:193], v219 offset:1568
	ds_read_b64 v[194:195], v220 offset:1024
	ds_read_b64 v[196:197], v220 offset:1056
	ds_read_b128 v[198:201], v119 offset:19584
	ds_read_b128 v[202:205], v119 offset:19648
	ds_read_b128 v[206:209], v119 offset:21888
	ds_read_b128 v[210:213], v119 offset:21952
	v_add_u32_e32 v178, s66, v155
	v_add_u32_sdwa v214, s66, v142 dst_sel:DWORD dst_unused:UNUSED_PAD src0_sel:DWORD src1_sel:BYTE_2
	v_add_u32_sdwa v215, s66, v142 dst_sel:DWORD dst_unused:UNUSED_PAD src0_sel:DWORD src1_sel:BYTE_3
	ds_read_b32 v136, v136 offset:41984
	ds_read_b32 v216, v162 offset:41984
	ds_read_b32 v163, v163 offset:41984
	ds_read_b32 v165, v165 offset:41984
	ds_read_b32 v217, v178 offset:41984
	ds_read_b32 v179, v179 offset:41984
	ds_read_b32 v221, v214 offset:41984
	ds_read_b32 v222, v215 offset:41984
	s_setprio 1
	s_waitcnt vmcnt(7) lgkmcnt(15)
	v_mfma_f32_16x16x32_bf16 v[158:161], v[158:161], v[80:83], 0
	s_waitcnt vmcnt(6)
	v_mfma_f32_16x16x32_bf16 v[158:161], v[166:169], v[84:87], v[158:161]
	v_mfma_f32_16x16x32_bf16 v[166:169], v[170:173], v[80:83], 0
	v_mfma_f32_16x16x32_bf16 v[166:169], v[174:177], v[84:87], v[166:169]
	s_setprio 0
	s_nop 6
	v_cndmask_b32_e64 v158, v166, v158, s[20:21]
	s_waitcnt lgkmcnt(7)
	v_add_f32_e32 v136, v136, v158
	v_exp_f32_e32 v162, v136
	v_cndmask_b32_e64 v136, v159, v167, s[10:11]
	v_cndmask_b32_e64 v159, v160, v168, s[12:13]
	s_waitcnt lgkmcnt(5)
	v_add_f32_e32 v159, v163, v159
	v_add_f32_e32 v136, v216, v136
	v_exp_f32_e32 v214, v159
	v_cndmask_b32_e64 v159, v161, v169, s[14:15]
	v_exp_f32_e32 v178, v136
	s_waitcnt lgkmcnt(4)
	v_add_f32_e32 v159, v165, v159
	v_exp_f32_e32 v216, v159
	s_nop 0
	v_cvt_pk_bf16_f32 v243, v162, v178
	v_cvt_pk_bf16_f32 v244, v214, v216
	v_and_b32_e32 v158, v243, v225
	v_and_b32_e32 v160, v243, v226
	v_and_b32_e32 v159, v244, v227
	v_and_b32_e32 v161, v244, v228
	s_setprio 1
	v_mfma_f32_16x16x32_bf16 v[60:63], v[182:185], v[158:161], v[60:63]
	v_mfma_f32_16x16x32_bf16 v[56:59], v[186:189], v[158:161], v[56:59]
	v_mfma_f32_16x16x32_bf16 v[52:55], v[190:193], v[158:161], v[52:55]
	v_mfma_f32_16x16x32_bf16 v[48:51], v[194:197], v[158:161], v[48:51]
	s_setprio 0
	ds_read_b64 v[158:159], v181 offset:1040
	ds_read_b64 v[160:161], v181 offset:1072
	ds_read_b64 v[166:167], v218 offset:1296
	ds_read_b64 v[168:169], v218 offset:1328
	ds_read_b64 v[170:171], v219 offset:1552
	ds_read_b64 v[172:173], v219 offset:1584
	ds_read_b64 v[174:175], v220 offset:1040
	ds_read_b64 v[176:177], v220 offset:1072
	ds_read_b128 v[182:185], v119 offset:21888
	ds_read_b128 v[186:189], v119 offset:21952
	ds_read_b128 v[190:193], v119 offset:24192
	ds_read_b128 v[194:197], v119 offset:24256
	v_add_u32_e32 v136, s66, v156
	v_add_u32_sdwa v165, s66, v140 dst_sel:DWORD dst_unused:UNUSED_PAD src0_sel:DWORD src1_sel:BYTE_2
	v_add_u32_sdwa v163, s66, v139 dst_sel:DWORD dst_unused:UNUSED_PAD src0_sel:DWORD src1_sel:BYTE_1
	v_add_u32_sdwa v215, s66, v140 dst_sel:DWORD dst_unused:UNUSED_PAD src0_sel:DWORD src1_sel:BYTE_3
	ds_read_b32 v136, v136 offset:41984
	ds_read_b32 v223, v163 offset:41984
	ds_read_b32 v165, v165 offset:41984
	ds_read_b32 v224, v215 offset:41984
	s_setprio 1
	s_waitcnt vmcnt(5)
	v_mfma_f32_16x16x32_bf16 v[198:201], v[198:201], v[88:91], 0
	s_waitcnt vmcnt(4)
	v_mfma_f32_16x16x32_bf16 v[198:201], v[202:205], v[92:95], v[198:201]
	v_mfma_f32_16x16x32_bf16 v[202:205], v[206:209], v[88:91], 0
	v_mfma_f32_16x16x32_bf16 v[202:205], v[210:213], v[92:95], v[202:205]
	s_setprio 0
	s_nop 6
	v_cndmask_b32_e64 v163, v198, v202, s[16:17]
	s_waitcnt lgkmcnt(15)
	v_add_f32_e32 v163, v217, v163
	v_cndmask_b32_e64 v198, v199, v203, s[18:19]
	v_cndmask_b32_e64 v200, v200, v204, s[6:7]
	v_exp_f32_e32 v163, v163
	v_add_f32_e32 v179, v179, v198
	s_waitcnt lgkmcnt(15)
	v_add_f32_e32 v200, v221, v200
	v_exp_f32_e32 v179, v179
	v_exp_f32_e32 v215, v200
	v_cndmask_b32_e64 v200, v201, v205, s[8:9]
	s_waitcnt lgkmcnt(15)
	v_add_f32_e32 v200, v222, v200
	v_exp_f32_e32 v217, v200
	s_nop 0
	v_cvt_pk_bf16_f32 v243, v163, v179
	v_cvt_pk_bf16_f32 v244, v215, v217
	v_pk_add_f32 v[162:163], v[162:163], 0 op_sel_hi:[1,0]
	v_pk_add_f32 v[162:163], v[178:179], v[162:163]
	v_pk_add_f32 v[162:163], v[214:215], v[162:163]
	v_pk_add_f32 v[162:163], v[216:217], v[162:163]
	v_pk_add_f32 v[130:131], v[130:131], v[162:163]
	v_and_b32_e32 v198, v243, v229
	v_and_b32_e32 v200, v243, v230
	v_and_b32_e32 v199, v244, v231
	v_and_b32_e32 v201, v244, v232
	s_setprio 1
	s_waitcnt lgkmcnt(14)
	v_mfma_f32_16x16x32_bf16 v[44:47], v[158:161], v[198:201], v[44:47]
	s_waitcnt lgkmcnt(12)
	v_mfma_f32_16x16x32_bf16 v[40:43], v[166:169], v[198:201], v[40:43]
	s_waitcnt lgkmcnt(10)
	v_mfma_f32_16x16x32_bf16 v[36:39], v[170:173], v[198:201], v[36:39]
	s_waitcnt lgkmcnt(8)
	v_mfma_f32_16x16x32_bf16 v[32:35], v[174:177], v[198:201], v[32:35]
	s_setprio 0
	ds_read_b64 v[158:159], v181 offset:1072
	ds_read_b64 v[160:161], v181 offset:1104
	ds_read_b64 v[166:167], v218 offset:1328
	ds_read_b64 v[168:169], v218 offset:1360
	ds_read_b64 v[170:171], v219 offset:1584
	ds_read_b64 v[172:173], v219 offset:1616
	ds_read_b64 v[174:175], v220 offset:1072
	ds_read_b64 v[176:177], v220 offset:1104
	ds_read_b128 v[198:201], v119 offset:23040
	ds_read_b128 v[202:205], v119 offset:23104
	v_add_u32_e32 v119, v148, v151
	ds_read_b128 v[206:209], v119 offset:18432
	ds_read_b128 v[210:213], v119 offset:18496
	v_add_u32_e32 v119, s66, v154
	v_add_u32_sdwa v162, s66, v144 dst_sel:DWORD dst_unused:UNUSED_PAD src0_sel:DWORD src1_sel:BYTE_1
	v_add_u32_sdwa v163, s66, v145 dst_sel:DWORD dst_unused:UNUSED_PAD src0_sel:DWORD src1_sel:BYTE_2
	v_add_u32_sdwa v178, s66, v145 dst_sel:DWORD dst_unused:UNUSED_PAD src0_sel:DWORD src1_sel:BYTE_3
	ds_read_b32 v119, v119 offset:41984
	ds_read_b32 v179, v162 offset:41984
	ds_read_b32 v214, v163 offset:41984
	ds_read_b32 v215, v178 offset:41984
	s_setprio 1
	s_waitcnt vmcnt(3) lgkmcnt(15)
	v_mfma_f32_16x16x32_bf16 v[182:185], v[182:185], v[96:99], 0
	s_waitcnt vmcnt(2)
	v_mfma_f32_16x16x32_bf16 v[182:185], v[186:189], v[100:103], v[182:185]
	v_mfma_f32_16x16x32_bf16 v[186:189], v[190:193], v[96:99], 0
	v_mfma_f32_16x16x32_bf16 v[186:189], v[194:197], v[100:103], v[186:189]
	s_setprio 0
	s_nop 6
	v_cndmask_b32_e64 v162, v186, v182, s[2:3]
	v_add_f32_e32 v136, v136, v162
	v_exp_f32_e32 v162, v136
	v_cndmask_b32_e64 v136, v187, v183, s[4:5]
	v_cndmask_b32_e64 v183, v184, v188, s[22:23]
	s_waitcnt lgkmcnt(15)
	v_add_f32_e32 v165, v165, v183
	v_exp_f32_e32 v190, v165
	v_cndmask_b32_e64 v165, v185, v189, s[24:25]
	v_add_f32_e32 v136, v223, v136
	s_waitcnt lgkmcnt(15)
	v_add_f32_e32 v165, v224, v165
	v_exp_f32_e32 v178, v136
	v_exp_f32_e32 v192, v165
	s_nop 0
	v_cvt_pk_bf16_f32 v243, v162, v178
	v_cvt_pk_bf16_f32 v244, v190, v192
	v_and_b32_e32 v182, v243, v233
	v_and_b32_e32 v184, v243, v234
	v_and_b32_e32 v183, v244, v235
	v_and_b32_e32 v185, v244, v236
	s_setprio 1
	s_waitcnt lgkmcnt(14)
	v_mfma_f32_16x16x32_bf16 v[28:31], v[158:161], v[182:185], v[28:31]
	s_waitcnt lgkmcnt(12)
	v_mfma_f32_16x16x32_bf16 v[24:27], v[166:169], v[182:185], v[24:27]
	s_waitcnt lgkmcnt(10)
	v_mfma_f32_16x16x32_bf16 v[20:23], v[170:173], v[182:185], v[20:23]
	s_waitcnt lgkmcnt(8)
	v_mfma_f32_16x16x32_bf16 v[16:19], v[174:177], v[182:185], v[16:19]
	s_setprio 0
	ds_read_b64 v[158:159], v220 offset:1088
	ds_read_b64 v[160:161], v220 offset:1120
	ds_read_b64 v[166:167], v219 offset:1600
	ds_read_b64 v[168:169], v219 offset:1632
	ds_read_b64 v[170:171], v218 offset:1344
	ds_read_b64 v[172:173], v218 offset:1376
	ds_read_b64 v[174:175], v181 offset:1088
	ds_read_b64 v[176:177], v181 offset:1120
	s_setprio 1
	s_waitcnt vmcnt(1) lgkmcnt(15)
	v_mfma_f32_16x16x32_bf16 v[182:185], v[198:201], v[104:107], 0
	s_waitcnt lgkmcnt(13)
	v_mfma_f32_16x16x32_bf16 v[186:189], v[206:209], v[104:107], 0
	s_waitcnt vmcnt(0)
	v_mfma_f32_16x16x32_bf16 v[182:185], v[202:205], v[108:111], v[182:185]
	s_waitcnt lgkmcnt(12)
	v_mfma_f32_16x16x32_bf16 v[186:189], v[210:213], v[108:111], v[186:189]
	s_setprio 0
	s_nop 6
	v_cndmask_b32_e64 v136, v182, v186, s[26:27]
	s_waitcnt lgkmcnt(11)
	v_add_f32_e32 v119, v119, v136
	v_exp_f32_e32 v163, v119
	v_cndmask_b32_e64 v119, v183, v187, s[28:29]
	v_cndmask_b32_e64 v181, v184, v188, s[30:31]
	s_waitcnt lgkmcnt(10)
	v_add_f32_e32 v119, v179, v119
	s_waitcnt lgkmcnt(9)
	v_add_f32_e32 v181, v214, v181
	v_exp_f32_e32 v179, v119
	v_exp_f32_e32 v191, v181
	v_cndmask_b32_e64 v181, v185, v189, s[34:35]
	s_waitcnt lgkmcnt(8)
	v_add_f32_e32 v181, v215, v181
	v_exp_f32_e32 v193, v181
	s_nop 0
	v_cvt_pk_bf16_f32 v243, v163, v179
	v_cvt_pk_bf16_f32 v244, v191, v193
	v_pk_add_f32 v[162:163], v[162:163], 0 op_sel_hi:[1,0]
	v_pk_add_f32 v[162:163], v[178:179], v[162:163]
	v_pk_add_f32 v[162:163], v[190:191], v[162:163]
	v_pk_add_f32 v[162:163], v[192:193], v[162:163]
	v_pk_add_f32 v[124:125], v[124:125], v[162:163]
	v_and_b32_e32 v182, v243, v237
	v_and_b32_e32 v184, v243, v238
	v_and_b32_e32 v183, v244, v239
	v_and_b32_e32 v185, v244, v240
	s_setprio 1
	s_waitcnt lgkmcnt(0)
	v_mfma_f32_16x16x32_bf16 v[12:15], v[174:177], v[182:185], v[12:15]
	v_mfma_f32_16x16x32_bf16 v[8:11], v[170:173], v[182:185], v[8:11]
	v_mfma_f32_16x16x32_bf16 v[4:7], v[166:169], v[182:185], v[4:7]
	v_mfma_f32_16x16x32_bf16 v[0:3], v[158:161], v[182:185], v[0:3]
	s_setprio 0

.LBB0_584:
	s_add_i32 s73, s38, s92
	s_lshl_b32 s38, s73, 6
	s_add_i32 s38, s38, s39
	v_add_u32_e32 v128, s38, v137
	s_lshl_b32 s38, s69, 1
	s_mov_b32 s39, s53
	v_ashrrev_i32_e32 v129, 31, v128
	v_lshl_add_u64 v[0:1], v[116:117], 0, s[38:39]
	v_lshlrev_b64 v[2:3], 10, v[128:129]
	v_add_u32_e32 v126, 16, v128
	v_lshl_add_u64 v[2:3], v[0:1], 0, v[2:3]
	v_ashrrev_i32_e32 v127, 31, v126
	global_load_dwordx4 v[80:83], v[2:3], off
	global_load_dwordx4 v[84:87], v[2:3], off offset:64
	v_lshlrev_b64 v[2:3], 10, v[126:127]
	v_add_u32_e32 v122, 32, v128
	v_lshl_add_u64 v[2:3], v[0:1], 0, v[2:3]
	v_ashrrev_i32_e32 v123, 31, v122
	global_load_dwordx4 v[88:91], v[2:3], off
	global_load_dwordx4 v[92:95], v[2:3], off offset:64
	v_lshlrev_b64 v[2:3], 10, v[122:123]
	v_add_u32_e32 v120, 48, v128
	v_lshl_add_u64 v[2:3], v[0:1], 0, v[2:3]
	v_ashrrev_i32_e32 v121, 31, v120
	global_load_dwordx4 v[96:99], v[2:3], off
	global_load_dwordx4 v[100:103], v[2:3], off offset:64
	v_lshlrev_b64 v[2:3], 10, v[120:121]
	v_lshl_add_u64 v[0:1], v[0:1], 0, v[2:3]
	global_load_dwordx4 v[104:107], v[0:1], off
	global_load_dwordx4 v[108:111], v[0:1], off offset:64
	v_mov_b32_e32 v131, 0
	s_andn2_b64 vcc, exec, s[70:71]
	v_mov_b32_e32 v130, 0
	v_mov_b32_e32 v125, 0
	v_mov_b32_e32 v124, 0
	v_mov_b32_e32 v63, 0
	v_mov_b32_e32 v62, 0
	v_mov_b32_e32 v61, 0
	v_mov_b32_e32 v60, 0
	v_mov_b32_e32 v59, 0
	v_mov_b32_e32 v58, 0
	v_mov_b32_e32 v57, 0
	v_mov_b32_e32 v56, 0
	v_mov_b32_e32 v55, 0
	v_mov_b32_e32 v54, 0
	v_mov_b32_e32 v53, 0
	v_mov_b32_e32 v52, 0
	v_mov_b32_e32 v51, 0
	v_mov_b32_e32 v50, 0
	v_mov_b32_e32 v49, 0
	v_mov_b32_e32 v48, 0
	v_mov_b32_e32 v47, 0
	v_mov_b32_e32 v46, 0
	v_mov_b32_e32 v45, 0
	v_mov_b32_e32 v44, 0
	v_mov_b32_e32 v43, 0
	v_mov_b32_e32 v42, 0
	v_mov_b32_e32 v41, 0
	v_mov_b32_e32 v40, 0
	v_mov_b32_e32 v39, 0
	v_mov_b32_e32 v38, 0
	v_mov_b32_e32 v37, 0
	v_mov_b32_e32 v36, 0
	v_mov_b32_e32 v35, 0
	v_mov_b32_e32 v34, 0
	v_mov_b32_e32 v33, 0
	v_mov_b32_e32 v32, 0
	v_mov_b32_e32 v31, 0
	v_mov_b32_e32 v30, 0
	v_mov_b32_e32 v29, 0
	v_mov_b32_e32 v28, 0
	v_mov_b32_e32 v27, 0
	v_mov_b32_e32 v26, 0
	v_mov_b32_e32 v25, 0
	v_mov_b32_e32 v24, 0
	v_mov_b32_e32 v23, 0
	v_mov_b32_e32 v22, 0
	v_mov_b32_e32 v21, 0
	v_mov_b32_e32 v20, 0
	v_mov_b32_e32 v19, 0
	v_mov_b32_e32 v18, 0
	v_mov_b32_e32 v17, 0
	v_mov_b32_e32 v16, 0
	v_mov_b32_e32 v15, 0
	v_mov_b32_e32 v14, 0
	v_mov_b32_e32 v13, 0
	v_mov_b32_e32 v12, 0
	v_mov_b32_e32 v11, 0
	v_mov_b32_e32 v10, 0
	v_mov_b32_e32 v9, 0
	v_mov_b32_e32 v8, 0
	v_mov_b32_e32 v7, 0
	v_mov_b32_e32 v6, 0
	v_mov_b32_e32 v5, 0
	v_mov_b32_e32 v4, 0
	v_mov_b32_e32 v3, 0
	v_mov_b32_e32 v2, 0
	v_mov_b32_e32 v1, 0
	v_mov_b32_e32 v0, 0
	v_mov_b32_e32 v241, 0xffff
	v_mov_b32_e32 v242, 0xffff0000
	v_cndmask_b32_e64 v243, 0, v241, s[20:21]
	v_cndmask_b32_e64 v244, v242, 0, s[10:11]
	v_or_b32_e32 v225, v243, v244
	v_cndmask_b32_e64 v243, v241, 0, s[20:21]
	v_cndmask_b32_e64 v244, 0, v242, s[10:11]
	v_or_b32_e32 v226, v243, v244
	v_cndmask_b32_e64 v243, v241, 0, s[12:13]
	v_cndmask_b32_e64 v244, v242, 0, s[14:15]
	v_or_b32_e32 v227, v243, v244
	v_cndmask_b32_e64 v243, 0, v241, s[12:13]
	v_cndmask_b32_e64 v244, 0, v242, s[14:15]
	v_or_b32_e32 v228, v243, v244
	v_cndmask_b32_e64 v243, v241, 0, s[16:17]
	v_cndmask_b32_e64 v244, v242, 0, s[18:19]
	v_or_b32_e32 v229, v243, v244
	v_cndmask_b32_e64 v243, 0, v241, s[16:17]
	v_cndmask_b32_e64 v244, 0, v242, s[18:19]
	v_or_b32_e32 v230, v243, v244
	v_cndmask_b32_e64 v243, v241, 0, s[6:7]
	v_cndmask_b32_e64 v244, v242, 0, s[8:9]
	v_or_b32_e32 v231, v243, v244
	v_cndmask_b32_e64 v243, 0, v241, s[6:7]
	v_cndmask_b32_e64 v244, 0, v242, s[8:9]
	v_or_b32_e32 v232, v243, v244
	v_cndmask_b32_e64 v243, 0, v241, s[2:3]
	v_cndmask_b32_e64 v244, 0, v242, s[4:5]
	v_or_b32_e32 v233, v243, v244
	v_cndmask_b32_e64 v243, v241, 0, s[2:3]
	v_cndmask_b32_e64 v244, v242, 0, s[4:5]
	v_or_b32_e32 v234, v243, v244
	v_cndmask_b32_e64 v243, v241, 0, s[22:23]
	v_cndmask_b32_e64 v244, v242, 0, s[24:25]
	v_or_b32_e32 v235, v243, v244
	v_cndmask_b32_e64 v243, 0, v241, s[22:23]
	v_cndmask_b32_e64 v244, 0, v242, s[24:25]
	v_or_b32_e32 v236, v243, v244
	v_cndmask_b32_e64 v243, v241, 0, s[26:27]
	v_cndmask_b32_e64 v244, v242, 0, s[28:29]
	v_or_b32_e32 v237, v243, v244
	v_cndmask_b32_e64 v243, 0, v241, s[26:27]
	v_cndmask_b32_e64 v244, 0, v242, s[28:29]
	v_or_b32_e32 v238, v243, v244
	v_cndmask_b32_e64 v243, v241, 0, s[30:31]
	v_cndmask_b32_e64 v244, v242, 0, s[34:35]
	v_or_b32_e32 v239, v243, v244
	v_cndmask_b32_e64 v243, 0, v241, s[30:31]
	v_cndmask_b32_e64 v244, 0, v242, s[34:35]
	v_or_b32_e32 v240, v243, v244
	s_waitcnt vmcnt(9)
	ds_write_b128 v157, v[64:67]
	s_waitcnt vmcnt(8)
	ds_write_b128 v157, v[68:71] offset:9216
	s_waitcnt lgkmcnt(0)
	s_barrier
	s_cbranch_vccnz .LBB0_601
	s_max_i32 s38, s73, 4
	s_add_i32 s38, s38, -4
	s_min_u32 s38, s38, s68
	s_mov_b32 s69, s53
	v_mov_b32_e32 v133, v113
	s_add_i32 s39, s38, 8
	v_mov_b32_e32 v0, s68
	v_cmp_lt_u64_e32 vcc, s[68:69], v[132:133]
	s_add_u32 s68, s80, s52
	v_mov_b32_e32 v1, v113
	v_cndmask_b32_e32 v2, v132, v0, vcc
	v_lshlrev_b32_e32 v0, 16, v2
	s_addc_u32 s69, s81, 0
	v_lshl_add_u64 v[0:1], s[68:69], 0, v[0:1]
	v_lshl_add_u64 v[132:133], v[0:1], 0, v[134:135]
	v_lshlrev_b32_e32 v0, 7, v2
	v_mov_b32_e32 v1, v113
	s_mul_i32 s70, s95, 0x780
	v_lshlrev_b32_e32 v2, 1, v136
	v_mov_b32_e32 v3, v113
	v_lshl_add_u64 v[0:1], s[66:67], 0, v[0:1]
	s_lshl_b32 s66, s72, 7
	v_lshl_add_u64 v[134:135], v[0:1], 0, v[2:3]
	s_add_i32 s70, s70, s66
	s_lshl_b32 s66, s73, 7
	v_mov_b32_e32 v2, v113
	s_sub_i32 s66, s70, s66
	v_mov_b32_e32 v124, v113
	v_mov_b32_e32 v125, v113
	v_mov_b32_e32 v0, v113
	v_mov_b32_e32 v1, v113
	v_mov_b64_e32 v[6:7], v[2:3]
	v_mov_b64_e32 v[10:11], v[2:3]
	v_mov_b64_e32 v[14:15], v[2:3]
	v_mov_b64_e32 v[18:19], v[2:3]
	v_mov_b64_e32 v[22:23], v[2:3]
	v_mov_b64_e32 v[26:27], v[2:3]
	v_mov_b64_e32 v[30:31], v[2:3]
	v_mov_b64_e32 v[34:35], v[2:3]
	v_mov_b64_e32 v[38:39], v[2:3]
	v_mov_b64_e32 v[42:43], v[2:3]
	v_mov_b64_e32 v[46:47], v[2:3]
	v_mov_b64_e32 v[50:51], v[2:3]
	v_mov_b64_e32 v[54:55], v[2:3]
	v_mov_b64_e32 v[58:59], v[2:3]
	v_mov_b64_e32 v[62:63], v[2:3]
	s_add_i32 s52, s72, 3
	s_add_i32 s68, s66, 0
	v_mov_b64_e32 v[4:5], v[0:1]
	v_mov_b64_e32 v[8:9], v[0:1]
	v_mov_b64_e32 v[12:13], v[0:1]
	v_mov_b64_e32 v[16:17], v[0:1]
	v_mov_b64_e32 v[20:21], v[0:1]
	v_mov_b64_e32 v[24:25], v[0:1]
	v_mov_b64_e32 v[28:29], v[0:1]
	v_mov_b64_e32 v[32:33], v[0:1]
	v_mov_b64_e32 v[36:37], v[0:1]
	v_mov_b64_e32 v[40:41], v[0:1]
	v_mov_b64_e32 v[44:45], v[0:1]
	v_mov_b64_e32 v[48:49], v[0:1]
	v_mov_b64_e32 v[52:53], v[0:1]
	v_mov_b64_e32 v[56:57], v[0:1]
	v_mov_b64_e32 v[60:61], v[0:1]
	v_mov_b64_e32 v[130:131], v[124:125]
	s_branch .LBB0_588

.LBB0_590:
	s_add_i32 s70, s52, -3
	s_cmp_ge_u32 s70, s38
	s_cselect_b64 s[66:67], -1, 0
	s_cmp_lt_u32 s70, s39
	s_cselect_b64 s[72:73], -1, 0
	s_and_b64 s[66:67], s[66:67], s[72:73]
	s_andn2_b64 vcc, exec, s[66:67]
	s_cbranch_vccnz .LBB0_592
	v_add_u32_e32 v178, v150, v149
	v_add_u32_e32 v181, 0x2000, v178
	v_add_u32_e32 v218, 0x2800, v178
	v_add_u32_e32 v219, 0x3000, v178
	v_add_u32_e32 v178, v150, v151
	v_add_u32_e32 v119, v148, v149
	v_add_u32_e32 v136, s68, v152
	v_add_u32_sdwa v163, s68, v144 dst_sel:DWORD dst_unused:UNUSED_PAD src0_sel:DWORD src1_sel:BYTE_2
	v_add_u32_sdwa v165, s68, v144 dst_sel:DWORD dst_unused:UNUSED_PAD src0_sel:DWORD src1_sel:BYTE_3
	v_add_u32_e32 v220, 0x2000, v178
	v_add_u32_sdwa v179, s68, v142 dst_sel:DWORD dst_unused:UNUSED_PAD src0_sel:DWORD src1_sel:BYTE_1
	ds_read_b128 v[158:161], v119
	ds_read_b128 v[166:169], v119 offset:64
	ds_read_b128 v[170:173], v119 offset:2304
	ds_read_b128 v[174:177], v119 offset:2368
	v_add_u32_e32 v162, s68, v153
	ds_read_b64 v[182:183], v181 offset:1024
	ds_read_b64 v[184:185], v181 offset:1056
	ds_read_b64 v[186:187], v218 offset:1280
	ds_read_b64 v[188:189], v218 offset:1312
	ds_read_b64 v[190:191], v219 offset:1536
	ds_read_b64 v[192:193], v219 offset:1568
	ds_read_b64 v[194:195], v220 offset:1024
	ds_read_b64 v[196:197], v220 offset:1056
	ds_read_b128 v[198:201], v119 offset:1152
	ds_read_b128 v[202:205], v119 offset:1216
	ds_read_b128 v[206:209], v119 offset:3456
	ds_read_b128 v[210:213], v119 offset:3520
	v_add_u32_e32 v178, s68, v155
	v_add_u32_sdwa v214, s68, v143 dst_sel:DWORD dst_unused:UNUSED_PAD src0_sel:DWORD src1_sel:BYTE_2
	v_add_u32_sdwa v215, s68, v143 dst_sel:DWORD dst_unused:UNUSED_PAD src0_sel:DWORD src1_sel:BYTE_3
	ds_read_b32 v136, v136 offset:41856
	ds_read_b32 v216, v162 offset:41856
	ds_read_b32 v163, v163 offset:41856
	ds_read_b32 v165, v165 offset:41856
	ds_read_b32 v217, v178 offset:41856
	ds_read_b32 v179, v179 offset:41856
	ds_read_b32 v221, v214 offset:41856
	ds_read_b32 v222, v215 offset:41856
	s_setprio 1
	s_waitcnt vmcnt(7) lgkmcnt(15)
	v_mfma_f32_16x16x32_bf16 v[158:161], v[158:161], v[80:83], 0
	s_waitcnt vmcnt(6)
	v_mfma_f32_16x16x32_bf16 v[158:161], v[166:169], v[84:87], v[158:161]
	v_mfma_f32_16x16x32_bf16 v[166:169], v[170:173], v[80:83], 0
	v_mfma_f32_16x16x32_bf16 v[166:169], v[174:177], v[84:87], v[166:169]
	s_setprio 0
	s_nop 6
	v_cndmask_b32_e64 v158, v166, v158, s[20:21]
	s_waitcnt lgkmcnt(7)
	v_add_f32_e32 v136, v136, v158
	v_exp_f32_e32 v162, v136
	v_cndmask_b32_e64 v136, v159, v167, s[10:11]
	v_cndmask_b32_e64 v159, v160, v168, s[12:13]
	s_waitcnt lgkmcnt(5)
	v_add_f32_e32 v159, v163, v159
	v_add_f32_e32 v136, v216, v136
	v_exp_f32_e32 v214, v159
	v_cndmask_b32_e64 v159, v161, v169, s[14:15]
	v_exp_f32_e32 v178, v136
	s_waitcnt lgkmcnt(4)
	v_add_f32_e32 v159, v165, v159
	v_exp_f32_e32 v216, v159
	s_nop 0
	v_cvt_pk_bf16_f32 v243, v162, v178
	v_cvt_pk_bf16_f32 v244, v214, v216
	v_and_b32_e32 v158, v243, v225
	v_and_b32_e32 v160, v243, v226
	v_and_b32_e32 v159, v244, v227
	v_and_b32_e32 v161, v244, v228
	s_setprio 1
	v_mfma_f32_16x16x32_bf16 v[60:63], v[182:185], v[158:161], v[60:63]
	v_mfma_f32_16x16x32_bf16 v[56:59], v[186:189], v[158:161], v[56:59]
	v_mfma_f32_16x16x32_bf16 v[52:55], v[190:193], v[158:161], v[52:55]
	v_mfma_f32_16x16x32_bf16 v[48:51], v[194:197], v[158:161], v[48:51]
	s_setprio 0
	ds_read_b64 v[158:159], v181 offset:1040
	ds_read_b64 v[160:161], v181 offset:1072
	ds_read_b64 v[166:167], v218 offset:1296
	ds_read_b64 v[168:169], v218 offset:1328
	ds_read_b64 v[170:171], v219 offset:1552
	ds_read_b64 v[172:173], v219 offset:1584
	ds_read_b64 v[174:175], v220 offset:1040
	ds_read_b64 v[176:177], v220 offset:1072
	ds_read_b128 v[182:185], v119 offset:3456
	ds_read_b128 v[186:189], v119 offset:3520
	ds_read_b128 v[190:193], v119 offset:5760
	ds_read_b128 v[194:197], v119 offset:5824
	v_add_u32_e32 v136, s68, v156
	v_add_u32_sdwa v165, s68, v141 dst_sel:DWORD dst_unused:UNUSED_PAD src0_sel:DWORD src1_sel:BYTE_2
	v_add_u32_sdwa v163, s68, v140 dst_sel:DWORD dst_unused:UNUSED_PAD src0_sel:DWORD src1_sel:BYTE_1
	v_add_u32_sdwa v215, s68, v141 dst_sel:DWORD dst_unused:UNUSED_PAD src0_sel:DWORD src1_sel:BYTE_3
	ds_read_b32 v136, v136 offset:41856
	ds_read_b32 v223, v163 offset:41856
	ds_read_b32 v165, v165 offset:41856
	ds_read_b32 v224, v215 offset:41856
	s_setprio 1
	s_waitcnt vmcnt(5)
	v_mfma_f32_16x16x32_bf16 v[198:201], v[198:201], v[88:91], 0
	s_waitcnt vmcnt(4)
	v_mfma_f32_16x16x32_bf16 v[198:201], v[202:205], v[92:95], v[198:201]
	v_mfma_f32_16x16x32_bf16 v[202:205], v[206:209], v[88:91], 0
	v_mfma_f32_16x16x32_bf16 v[202:205], v[210:213], v[92:95], v[202:205]
	s_setprio 0
	s_nop 6
	v_cndmask_b32_e64 v163, v198, v202, s[16:17]
	s_waitcnt lgkmcnt(15)
	v_add_f32_e32 v163, v217, v163
	v_cndmask_b32_e64 v198, v199, v203, s[18:19]
	v_cndmask_b32_e64 v200, v200, v204, s[6:7]
	v_exp_f32_e32 v163, v163
	v_add_f32_e32 v179, v179, v198
	s_waitcnt lgkmcnt(15)
	v_add_f32_e32 v200, v221, v200
	v_exp_f32_e32 v179, v179
	v_exp_f32_e32 v215, v200
	v_cndmask_b32_e64 v200, v201, v205, s[8:9]
	s_waitcnt lgkmcnt(15)
	v_add_f32_e32 v200, v222, v200
	v_exp_f32_e32 v217, v200
	s_nop 0
	v_cvt_pk_bf16_f32 v243, v163, v179
	v_cvt_pk_bf16_f32 v244, v215, v217
	v_pk_add_f32 v[162:163], v[162:163], 0 op_sel_hi:[1,0]
	v_pk_add_f32 v[162:163], v[178:179], v[162:163]
	v_pk_add_f32 v[162:163], v[214:215], v[162:163]
	v_pk_add_f32 v[162:163], v[216:217], v[162:163]
	v_pk_add_f32 v[130:131], v[130:131], v[162:163]
	v_and_b32_e32 v198, v243, v229
	v_and_b32_e32 v200, v243, v230
	v_and_b32_e32 v199, v244, v231
	v_and_b32_e32 v201, v244, v232
	s_setprio 1
	s_waitcnt lgkmcnt(14)
	v_mfma_f32_16x16x32_bf16 v[44:47], v[158:161], v[198:201], v[44:47]
	s_waitcnt lgkmcnt(12)
	v_mfma_f32_16x16x32_bf16 v[40:43], v[166:169], v[198:201], v[40:43]
	s_waitcnt lgkmcnt(10)
	v_mfma_f32_16x16x32_bf16 v[36:39], v[170:173], v[198:201], v[36:39]
	s_waitcnt lgkmcnt(8)
	v_mfma_f32_16x16x32_bf16 v[32:35], v[174:177], v[198:201], v[32:35]
	s_setprio 0
	ds_read_b64 v[158:159], v181 offset:1072
	ds_read_b64 v[160:161], v181 offset:1104
	ds_read_b64 v[166:167], v218 offset:1328
	ds_read_b64 v[168:169], v218 offset:1360
	ds_read_b64 v[170:171], v219 offset:1584
	ds_read_b64 v[172:173], v219 offset:1616
	ds_read_b64 v[174:175], v220 offset:1072
	ds_read_b64 v[176:177], v220 offset:1104
	ds_read_b128 v[198:201], v119 offset:4608
	ds_read_b128 v[202:205], v119 offset:4672
	v_add_u32_e32 v119, v148, v151
	ds_read_b128 v[206:209], v119
	ds_read_b128 v[210:213], v119 offset:64
	v_add_u32_e32 v119, s68, v154
	v_add_u32_sdwa v162, s68, v145 dst_sel:DWORD dst_unused:UNUSED_PAD src0_sel:DWORD src1_sel:BYTE_1
	v_add_u32_sdwa v163, s68, v146 dst_sel:DWORD dst_unused:UNUSED_PAD src0_sel:DWORD src1_sel:BYTE_2
	v_add_u32_sdwa v178, s68, v146 dst_sel:DWORD dst_unused:UNUSED_PAD src0_sel:DWORD src1_sel:BYTE_3
	ds_read_b32 v119, v119 offset:41856
	ds_read_b32 v179, v162 offset:41856
	ds_read_b32 v214, v163 offset:41856
	ds_read_b32 v215, v178 offset:41856
	s_setprio 1
	s_waitcnt vmcnt(3) lgkmcnt(15)
	v_mfma_f32_16x16x32_bf16 v[182:185], v[182:185], v[96:99], 0
	s_waitcnt vmcnt(2)
	v_mfma_f32_16x16x32_bf16 v[182:185], v[186:189], v[100:103], v[182:185]
	v_mfma_f32_16x16x32_bf16 v[186:189], v[190:193], v[96:99], 0
	v_mfma_f32_16x16x32_bf16 v[186:189], v[194:197], v[100:103], v[186:189]
	s_setprio 0
	s_nop 6
	v_cndmask_b32_e64 v162, v186, v182, s[2:3]
	v_add_f32_e32 v136, v136, v162
	v_exp_f32_e32 v162, v136
	v_cndmask_b32_e64 v136, v187, v183, s[4:5]
	v_cndmask_b32_e64 v183, v184, v188, s[22:23]
	s_waitcnt lgkmcnt(15)
	v_add_f32_e32 v165, v165, v183
	v_exp_f32_e32 v190, v165
	v_cndmask_b32_e64 v165, v185, v189, s[24:25]
	v_add_f32_e32 v136, v223, v136
	s_waitcnt lgkmcnt(15)
	v_add_f32_e32 v165, v224, v165
	v_exp_f32_e32 v178, v136
	v_exp_f32_e32 v192, v165
	s_nop 0
	v_cvt_pk_bf16_f32 v243, v162, v178
	v_cvt_pk_bf16_f32 v244, v190, v192
	v_and_b32_e32 v182, v243, v233
	v_and_b32_e32 v184, v243, v234
	v_and_b32_e32 v183, v244, v235
	v_and_b32_e32 v185, v244, v236
	s_setprio 1
	s_waitcnt lgkmcnt(14)
	v_mfma_f32_16x16x32_bf16 v[28:31], v[158:161], v[182:185], v[28:31]
	s_waitcnt lgkmcnt(12)
	v_mfma_f32_16x16x32_bf16 v[24:27], v[166:169], v[182:185], v[24:27]
	s_waitcnt lgkmcnt(10)
	v_mfma_f32_16x16x32_bf16 v[20:23], v[170:173], v[182:185], v[20:23]
	s_waitcnt lgkmcnt(8)
	v_mfma_f32_16x16x32_bf16 v[16:19], v[174:177], v[182:185], v[16:19]
	s_setprio 0
	ds_read_b64 v[158:159], v220 offset:1088
	ds_read_b64 v[160:161], v220 offset:1120
	ds_read_b64 v[166:167], v219 offset:1600
	ds_read_b64 v[168:169], v219 offset:1632
	ds_read_b64 v[170:171], v218 offset:1344
	ds_read_b64 v[172:173], v218 offset:1376
	ds_read_b64 v[174:175], v181 offset:1088
	ds_read_b64 v[176:177], v181 offset:1120
	s_setprio 1
	s_waitcnt vmcnt(1) lgkmcnt(15)
	v_mfma_f32_16x16x32_bf16 v[182:185], v[198:201], v[104:107], 0
	s_waitcnt lgkmcnt(13)
	v_mfma_f32_16x16x32_bf16 v[186:189], v[206:209], v[104:107], 0
	s_waitcnt vmcnt(0)
	v_mfma_f32_16x16x32_bf16 v[182:185], v[202:205], v[108:111], v[182:185]
	s_waitcnt lgkmcnt(12)
	v_mfma_f32_16x16x32_bf16 v[186:189], v[210:213], v[108:111], v[186:189]
	s_setprio 0
	s_nop 6
	v_cndmask_b32_e64 v136, v182, v186, s[26:27]
	s_waitcnt lgkmcnt(11)
	v_add_f32_e32 v119, v119, v136
	v_exp_f32_e32 v163, v119
	v_cndmask_b32_e64 v119, v183, v187, s[28:29]
	v_cndmask_b32_e64 v181, v184, v188, s[30:31]
	s_waitcnt lgkmcnt(10)
	v_add_f32_e32 v119, v179, v119
	s_waitcnt lgkmcnt(9)
	v_add_f32_e32 v181, v214, v181
	v_exp_f32_e32 v179, v119
	v_exp_f32_e32 v191, v181
	v_cndmask_b32_e64 v181, v185, v189, s[34:35]
	s_waitcnt lgkmcnt(8)
	v_add_f32_e32 v181, v215, v181
	v_exp_f32_e32 v193, v181
	s_nop 0
	v_cvt_pk_bf16_f32 v243, v163, v179
	v_cvt_pk_bf16_f32 v244, v191, v193
	v_pk_add_f32 v[162:163], v[162:163], 0 op_sel_hi:[1,0]
	v_pk_add_f32 v[162:163], v[178:179], v[162:163]
	v_pk_add_f32 v[162:163], v[190:191], v[162:163]
	v_pk_add_f32 v[162:163], v[192:193], v[162:163]
	v_pk_add_f32 v[124:125], v[124:125], v[162:163]
	v_and_b32_e32 v182, v243, v237
	v_and_b32_e32 v184, v243, v238
	v_and_b32_e32 v183, v244, v239
	v_and_b32_e32 v185, v244, v240
	s_setprio 1
	s_waitcnt lgkmcnt(0)
	v_mfma_f32_16x16x32_bf16 v[12:15], v[174:177], v[182:185], v[12:15]
	v_mfma_f32_16x16x32_bf16 v[8:11], v[170:173], v[182:185], v[8:11]
	v_mfma_f32_16x16x32_bf16 v[4:7], v[166:169], v[182:185], v[4:7]
	v_mfma_f32_16x16x32_bf16 v[0:3], v[158:161], v[182:185], v[0:3]
	s_setprio 0

.LBB0_597:
	s_add_i32 s66, s52, -2
	s_cmp_ge_u32 s66, s38
	s_cselect_b64 s[70:71], -1, 0
	s_cmp_lt_u32 s66, s39
	s_cselect_b64 s[72:73], -1, 0
	s_and_b64 s[70:71], s[70:71], s[72:73]
	s_andn2_b64 vcc, exec, s[70:71]
	s_cbranch_vccnz .LBB0_599
	v_add_u32_e32 v178, v150, v149
	v_add_u32_e32 v181, 0x6800, v178
	v_add_u32_e32 v218, 0x7000, v178
	v_add_u32_e32 v219, 0x7800, v178
	v_add_u32_e32 v178, v150, v151
	v_add_u32_e32 v119, v148, v149
	v_add_u32_e32 v136, s68, v152
	v_add_u32_sdwa v163, s68, v144 dst_sel:DWORD dst_unused:UNUSED_PAD src0_sel:DWORD src1_sel:BYTE_2
	v_add_u32_sdwa v165, s68, v144 dst_sel:DWORD dst_unused:UNUSED_PAD src0_sel:DWORD src1_sel:BYTE_3
	v_add_u32_e32 v220, 0x6800, v178
	v_add_u32_sdwa v179, s68, v142 dst_sel:DWORD dst_unused:UNUSED_PAD src0_sel:DWORD src1_sel:BYTE_1
	ds_read_b128 v[158:161], v119 offset:18432
	ds_read_b128 v[166:169], v119 offset:18496
	ds_read_b128 v[170:173], v119 offset:20736
	ds_read_b128 v[174:177], v119 offset:20800
	v_add_u32_e32 v162, s68, v153
	ds_read_b64 v[182:183], v181 offset:1024
	ds_read_b64 v[184:185], v181 offset:1056
	ds_read_b64 v[186:187], v218 offset:1280
	ds_read_b64 v[188:189], v218 offset:1312
	ds_read_b64 v[190:191], v219 offset:1536
	ds_read_b64 v[192:193], v219 offset:1568
	ds_read_b64 v[194:195], v220 offset:1024
	ds_read_b64 v[196:197], v220 offset:1056
	ds_read_b128 v[198:201], v119 offset:19584
	ds_read_b128 v[202:205], v119 offset:19648
	ds_read_b128 v[206:209], v119 offset:21888
	ds_read_b128 v[210:213], v119 offset:21952
	v_add_u32_e32 v178, s68, v155
	v_add_u32_sdwa v214, s68, v143 dst_sel:DWORD dst_unused:UNUSED_PAD src0_sel:DWORD src1_sel:BYTE_2
	v_add_u32_sdwa v215, s68, v143 dst_sel:DWORD dst_unused:UNUSED_PAD src0_sel:DWORD src1_sel:BYTE_3
	ds_read_b32 v136, v136 offset:41984
	ds_read_b32 v216, v162 offset:41984
	ds_read_b32 v163, v163 offset:41984
	ds_read_b32 v165, v165 offset:41984
	ds_read_b32 v217, v178 offset:41984
	ds_read_b32 v179, v179 offset:41984
	ds_read_b32 v221, v214 offset:41984
	ds_read_b32 v222, v215 offset:41984
	s_setprio 1
	s_waitcnt vmcnt(7) lgkmcnt(15)
	v_mfma_f32_16x16x32_bf16 v[158:161], v[158:161], v[80:83], 0
	s_waitcnt vmcnt(6)
	v_mfma_f32_16x16x32_bf16 v[158:161], v[166:169], v[84:87], v[158:161]
	v_mfma_f32_16x16x32_bf16 v[166:169], v[170:173], v[80:83], 0
	v_mfma_f32_16x16x32_bf16 v[166:169], v[174:177], v[84:87], v[166:169]
	s_setprio 0
	s_nop 6
	v_cndmask_b32_e64 v158, v166, v158, s[20:21]
	s_waitcnt lgkmcnt(7)
	v_add_f32_e32 v136, v136, v158
	v_exp_f32_e32 v162, v136
	v_cndmask_b32_e64 v136, v159, v167, s[10:11]
	v_cndmask_b32_e64 v159, v160, v168, s[12:13]
	s_waitcnt lgkmcnt(5)
	v_add_f32_e32 v159, v163, v159
	v_add_f32_e32 v136, v216, v136
	v_exp_f32_e32 v214, v159
	v_cndmask_b32_e64 v159, v161, v169, s[14:15]
	v_exp_f32_e32 v178, v136
	s_waitcnt lgkmcnt(4)
	v_add_f32_e32 v159, v165, v159
	v_exp_f32_e32 v216, v159
	s_nop 0
	v_cvt_pk_bf16_f32 v243, v162, v178
	v_cvt_pk_bf16_f32 v244, v214, v216
	v_and_b32_e32 v158, v243, v225
	v_and_b32_e32 v160, v243, v226
	v_and_b32_e32 v159, v244, v227
	v_and_b32_e32 v161, v244, v228
	s_setprio 1
	v_mfma_f32_16x16x32_bf16 v[60:63], v[182:185], v[158:161], v[60:63]
	v_mfma_f32_16x16x32_bf16 v[56:59], v[186:189], v[158:161], v[56:59]
	v_mfma_f32_16x16x32_bf16 v[52:55], v[190:193], v[158:161], v[52:55]
	v_mfma_f32_16x16x32_bf16 v[48:51], v[194:197], v[158:161], v[48:51]
	s_setprio 0
	ds_read_b64 v[158:159], v181 offset:1040
	ds_read_b64 v[160:161], v181 offset:1072
	ds_read_b64 v[166:167], v218 offset:1296
	ds_read_b64 v[168:169], v218 offset:1328
	ds_read_b64 v[170:171], v219 offset:1552
	ds_read_b64 v[172:173], v219 offset:1584
	ds_read_b64 v[174:175], v220 offset:1040
	ds_read_b64 v[176:177], v220 offset:1072
	ds_read_b128 v[182:185], v119 offset:21888
	ds_read_b128 v[186:189], v119 offset:21952
	ds_read_b128 v[190:193], v119 offset:24192
	ds_read_b128 v[194:197], v119 offset:24256
	v_add_u32_e32 v136, s68, v156
	v_add_u32_sdwa v165, s68, v141 dst_sel:DWORD dst_unused:UNUSED_PAD src0_sel:DWORD src1_sel:BYTE_2
	v_add_u32_sdwa v163, s68, v140 dst_sel:DWORD dst_unused:UNUSED_PAD src0_sel:DWORD src1_sel:BYTE_1
	v_add_u32_sdwa v215, s68, v141 dst_sel:DWORD dst_unused:UNUSED_PAD src0_sel:DWORD src1_sel:BYTE_3
	ds_read_b32 v136, v136 offset:41984
	ds_read_b32 v223, v163 offset:41984
	ds_read_b32 v165, v165 offset:41984
	ds_read_b32 v224, v215 offset:41984
	s_setprio 1
	s_waitcnt vmcnt(5)
	v_mfma_f32_16x16x32_bf16 v[198:201], v[198:201], v[88:91], 0
	s_waitcnt vmcnt(4)
	v_mfma_f32_16x16x32_bf16 v[198:201], v[202:205], v[92:95], v[198:201]
	v_mfma_f32_16x16x32_bf16 v[202:205], v[206:209], v[88:91], 0
	v_mfma_f32_16x16x32_bf16 v[202:205], v[210:213], v[92:95], v[202:205]
	s_setprio 0
	s_nop 6
	v_cndmask_b32_e64 v163, v198, v202, s[16:17]
	s_waitcnt lgkmcnt(15)
	v_add_f32_e32 v163, v217, v163
	v_cndmask_b32_e64 v198, v199, v203, s[18:19]
	v_cndmask_b32_e64 v200, v200, v204, s[6:7]
	v_exp_f32_e32 v163, v163
	v_add_f32_e32 v179, v179, v198
	s_waitcnt lgkmcnt(15)
	v_add_f32_e32 v200, v221, v200
	v_exp_f32_e32 v179, v179
	v_exp_f32_e32 v215, v200
	v_cndmask_b32_e64 v200, v201, v205, s[8:9]
	s_waitcnt lgkmcnt(15)
	v_add_f32_e32 v200, v222, v200
	v_exp_f32_e32 v217, v200
	s_nop 0
	v_cvt_pk_bf16_f32 v243, v163, v179
	v_cvt_pk_bf16_f32 v244, v215, v217
	v_pk_add_f32 v[162:163], v[162:163], 0 op_sel_hi:[1,0]
	v_pk_add_f32 v[162:163], v[178:179], v[162:163]
	v_pk_add_f32 v[162:163], v[214:215], v[162:163]
	v_pk_add_f32 v[162:163], v[216:217], v[162:163]
	v_pk_add_f32 v[130:131], v[130:131], v[162:163]
	v_and_b32_e32 v198, v243, v229
	v_and_b32_e32 v200, v243, v230
	v_and_b32_e32 v199, v244, v231
	v_and_b32_e32 v201, v244, v232
	s_setprio 1
	s_waitcnt lgkmcnt(14)
	v_mfma_f32_16x16x32_bf16 v[44:47], v[158:161], v[198:201], v[44:47]
	s_waitcnt lgkmcnt(12)
	v_mfma_f32_16x16x32_bf16 v[40:43], v[166:169], v[198:201], v[40:43]
	s_waitcnt lgkmcnt(10)
	v_mfma_f32_16x16x32_bf16 v[36:39], v[170:173], v[198:201], v[36:39]
	s_waitcnt lgkmcnt(8)
	v_mfma_f32_16x16x32_bf16 v[32:35], v[174:177], v[198:201], v[32:35]
	s_setprio 0
	ds_read_b64 v[158:159], v181 offset:1072
	ds_read_b64 v[160:161], v181 offset:1104
	ds_read_b64 v[166:167], v218 offset:1328
	ds_read_b64 v[168:169], v218 offset:1360
	ds_read_b64 v[170:171], v219 offset:1584
	ds_read_b64 v[172:173], v219 offset:1616
	ds_read_b64 v[174:175], v220 offset:1072
	ds_read_b64 v[176:177], v220 offset:1104
	ds_read_b128 v[198:201], v119 offset:23040
	ds_read_b128 v[202:205], v119 offset:23104
	v_add_u32_e32 v119, v148, v151
	ds_read_b128 v[206:209], v119 offset:18432
	ds_read_b128 v[210:213], v119 offset:18496
	v_add_u32_e32 v119, s68, v154
	v_add_u32_sdwa v162, s68, v145 dst_sel:DWORD dst_unused:UNUSED_PAD src0_sel:DWORD src1_sel:BYTE_1
	v_add_u32_sdwa v163, s68, v146 dst_sel:DWORD dst_unused:UNUSED_PAD src0_sel:DWORD src1_sel:BYTE_2
	v_add_u32_sdwa v178, s68, v146 dst_sel:DWORD dst_unused:UNUSED_PAD src0_sel:DWORD src1_sel:BYTE_3
	ds_read_b32 v119, v119 offset:41984
	ds_read_b32 v179, v162 offset:41984
	ds_read_b32 v214, v163 offset:41984
	ds_read_b32 v215, v178 offset:41984
	s_setprio 1
	s_waitcnt vmcnt(3) lgkmcnt(15)
	v_mfma_f32_16x16x32_bf16 v[182:185], v[182:185], v[96:99], 0
	s_waitcnt vmcnt(2)
	v_mfma_f32_16x16x32_bf16 v[182:185], v[186:189], v[100:103], v[182:185]
	v_mfma_f32_16x16x32_bf16 v[186:189], v[190:193], v[96:99], 0
	v_mfma_f32_16x16x32_bf16 v[186:189], v[194:197], v[100:103], v[186:189]
	s_setprio 0
	s_nop 6
	v_cndmask_b32_e64 v162, v186, v182, s[2:3]
	v_add_f32_e32 v136, v136, v162
	v_exp_f32_e32 v162, v136
	v_cndmask_b32_e64 v136, v187, v183, s[4:5]
	v_cndmask_b32_e64 v183, v184, v188, s[22:23]
	s_waitcnt lgkmcnt(15)
	v_add_f32_e32 v165, v165, v183
	v_exp_f32_e32 v190, v165
	v_cndmask_b32_e64 v165, v185, v189, s[24:25]
	v_add_f32_e32 v136, v223, v136
	s_waitcnt lgkmcnt(15)
	v_add_f32_e32 v165, v224, v165
	v_exp_f32_e32 v178, v136
	v_exp_f32_e32 v192, v165
	s_nop 0
	v_cvt_pk_bf16_f32 v243, v162, v178
	v_cvt_pk_bf16_f32 v244, v190, v192
	v_and_b32_e32 v182, v243, v233
	v_and_b32_e32 v184, v243, v234
	v_and_b32_e32 v183, v244, v235
	v_and_b32_e32 v185, v244, v236
	s_setprio 1
	s_waitcnt lgkmcnt(14)
	v_mfma_f32_16x16x32_bf16 v[28:31], v[158:161], v[182:185], v[28:31]
	s_waitcnt lgkmcnt(12)
	v_mfma_f32_16x16x32_bf16 v[24:27], v[166:169], v[182:185], v[24:27]
	s_waitcnt lgkmcnt(10)
	v_mfma_f32_16x16x32_bf16 v[20:23], v[170:173], v[182:185], v[20:23]
	s_waitcnt lgkmcnt(8)
	v_mfma_f32_16x16x32_bf16 v[16:19], v[174:177], v[182:185], v[16:19]
	s_setprio 0
	ds_read_b64 v[158:159], v220 offset:1088
	ds_read_b64 v[160:161], v220 offset:1120
	ds_read_b64 v[166:167], v219 offset:1600
	ds_read_b64 v[168:169], v219 offset:1632
	ds_read_b64 v[170:171], v218 offset:1344
	ds_read_b64 v[172:173], v218 offset:1376
	ds_read_b64 v[174:175], v181 offset:1088
	ds_read_b64 v[176:177], v181 offset:1120
	s_setprio 1
	s_waitcnt vmcnt(1) lgkmcnt(15)
	v_mfma_f32_16x16x32_bf16 v[182:185], v[198:201], v[104:107], 0
	s_waitcnt lgkmcnt(13)
	v_mfma_f32_16x16x32_bf16 v[186:189], v[206:209], v[104:107], 0
	s_waitcnt vmcnt(0)
	v_mfma_f32_16x16x32_bf16 v[182:185], v[202:205], v[108:111], v[182:185]
	s_waitcnt lgkmcnt(12)
	v_mfma_f32_16x16x32_bf16 v[186:189], v[210:213], v[108:111], v[186:189]
	s_setprio 0
	s_nop 6
	v_cndmask_b32_e64 v136, v182, v186, s[26:27]
	s_waitcnt lgkmcnt(11)
	v_add_f32_e32 v119, v119, v136
	v_exp_f32_e32 v163, v119
	v_cndmask_b32_e64 v119, v183, v187, s[28:29]
	v_cndmask_b32_e64 v181, v184, v188, s[30:31]
	s_waitcnt lgkmcnt(10)
	v_add_f32_e32 v119, v179, v119
	s_waitcnt lgkmcnt(9)
	v_add_f32_e32 v181, v214, v181
	v_exp_f32_e32 v179, v119
	v_exp_f32_e32 v191, v181
	v_cndmask_b32_e64 v181, v185, v189, s[34:35]
	s_waitcnt lgkmcnt(8)
	v_add_f32_e32 v181, v215, v181
	v_exp_f32_e32 v193, v181
	s_nop 0
	v_cvt_pk_bf16_f32 v243, v163, v179
	v_cvt_pk_bf16_f32 v244, v191, v193
	v_pk_add_f32 v[162:163], v[162:163], 0 op_sel_hi:[1,0]
	v_pk_add_f32 v[162:163], v[178:179], v[162:163]
	v_pk_add_f32 v[162:163], v[190:191], v[162:163]
	v_pk_add_f32 v[162:163], v[192:193], v[162:163]
	v_pk_add_f32 v[124:125], v[124:125], v[162:163]
	v_and_b32_e32 v182, v243, v237
	v_and_b32_e32 v184, v243, v238
	v_and_b32_e32 v183, v244, v239
	v_and_b32_e32 v185, v244, v240
	s_setprio 1
	s_waitcnt lgkmcnt(0)
	v_mfma_f32_16x16x32_bf16 v[12:15], v[174:177], v[182:185], v[12:15]
	v_mfma_f32_16x16x32_bf16 v[8:11], v[170:173], v[182:185], v[8:11]
	v_mfma_f32_16x16x32_bf16 v[4:7], v[166:169], v[182:185], v[4:7]
	v_mfma_f32_16x16x32_bf16 v[0:3], v[158:161], v[182:185], v[0:3]
	s_setprio 0

.LBB0_684:
	s_add_i32 s74, s38, s92
	s_lshl_b32 s38, s74, 6
	s_add_i32 s38, s38, s39
	v_add_u32_e32 v128, s38, v137
	s_lshl_b32 s38, s61, 1
	s_mov_b32 s39, s41
	v_ashrrev_i32_e32 v129, 31, v128
	v_lshl_add_u64 v[0:1], v[116:117], 0, s[38:39]
	v_lshlrev_b64 v[2:3], 10, v[128:129]
	v_add_u32_e32 v126, 16, v128
	v_lshl_add_u64 v[2:3], v[0:1], 0, v[2:3]
	v_ashrrev_i32_e32 v127, 31, v126
	global_load_dwordx4 v[80:83], v[2:3], off
	global_load_dwordx4 v[84:87], v[2:3], off offset:64
	v_lshlrev_b64 v[2:3], 10, v[126:127]
	v_add_u32_e32 v122, 32, v128
	v_lshl_add_u64 v[2:3], v[0:1], 0, v[2:3]
	v_ashrrev_i32_e32 v123, 31, v122
	global_load_dwordx4 v[88:91], v[2:3], off
	global_load_dwordx4 v[92:95], v[2:3], off offset:64
	v_lshlrev_b64 v[2:3], 10, v[122:123]
	v_add_u32_e32 v120, 48, v128
	v_lshl_add_u64 v[2:3], v[0:1], 0, v[2:3]
	v_ashrrev_i32_e32 v121, 31, v120
	global_load_dwordx4 v[96:99], v[2:3], off
	global_load_dwordx4 v[100:103], v[2:3], off offset:64
	v_lshlrev_b64 v[2:3], 10, v[120:121]
	v_lshl_add_u64 v[0:1], v[0:1], 0, v[2:3]
	global_load_dwordx4 v[104:107], v[0:1], off
	global_load_dwordx4 v[108:111], v[0:1], off offset:64
	v_mov_b32_e32 v131, 0
	s_andn2_b64 vcc, exec, s[62:63]
	v_mov_b32_e32 v130, 0
	v_mov_b32_e32 v125, 0
	v_mov_b32_e32 v124, 0
	v_mov_b32_e32 v63, 0
	v_mov_b32_e32 v62, 0
	v_mov_b32_e32 v61, 0
	v_mov_b32_e32 v60, 0
	v_mov_b32_e32 v59, 0
	v_mov_b32_e32 v58, 0
	v_mov_b32_e32 v57, 0
	v_mov_b32_e32 v56, 0
	v_mov_b32_e32 v55, 0
	v_mov_b32_e32 v54, 0
	v_mov_b32_e32 v53, 0
	v_mov_b32_e32 v52, 0
	v_mov_b32_e32 v51, 0
	v_mov_b32_e32 v50, 0
	v_mov_b32_e32 v49, 0
	v_mov_b32_e32 v48, 0
	v_mov_b32_e32 v47, 0
	v_mov_b32_e32 v46, 0
	v_mov_b32_e32 v45, 0
	v_mov_b32_e32 v44, 0
	v_mov_b32_e32 v43, 0
	v_mov_b32_e32 v42, 0
	v_mov_b32_e32 v41, 0
	v_mov_b32_e32 v40, 0
	v_mov_b32_e32 v39, 0
	v_mov_b32_e32 v38, 0
	v_mov_b32_e32 v37, 0
	v_mov_b32_e32 v36, 0
	v_mov_b32_e32 v35, 0
	v_mov_b32_e32 v34, 0
	v_mov_b32_e32 v33, 0
	v_mov_b32_e32 v32, 0
	v_mov_b32_e32 v31, 0
	v_mov_b32_e32 v30, 0
	v_mov_b32_e32 v29, 0
	v_mov_b32_e32 v28, 0
	v_mov_b32_e32 v27, 0
	v_mov_b32_e32 v26, 0
	v_mov_b32_e32 v25, 0
	v_mov_b32_e32 v24, 0
	v_mov_b32_e32 v23, 0
	v_mov_b32_e32 v22, 0
	v_mov_b32_e32 v21, 0
	v_mov_b32_e32 v20, 0
	v_mov_b32_e32 v19, 0
	v_mov_b32_e32 v18, 0
	v_mov_b32_e32 v17, 0
	v_mov_b32_e32 v16, 0
	v_mov_b32_e32 v15, 0
	v_mov_b32_e32 v14, 0
	v_mov_b32_e32 v13, 0
	v_mov_b32_e32 v12, 0
	v_mov_b32_e32 v11, 0
	v_mov_b32_e32 v10, 0
	v_mov_b32_e32 v9, 0
	v_mov_b32_e32 v8, 0
	v_mov_b32_e32 v7, 0
	v_mov_b32_e32 v6, 0
	v_mov_b32_e32 v5, 0
	v_mov_b32_e32 v4, 0
	v_mov_b32_e32 v3, 0
	v_mov_b32_e32 v2, 0
	v_mov_b32_e32 v1, 0
	v_mov_b32_e32 v0, 0
	v_mov_b32_e32 v241, 0xffff
	v_mov_b32_e32 v242, 0xffff0000
	v_cndmask_b32_e64 v243, 0, v241, s[20:21]
	v_cndmask_b32_e64 v244, v242, 0, s[10:11]
	v_or_b32_e32 v225, v243, v244
	v_cndmask_b32_e64 v243, v241, 0, s[20:21]
	v_cndmask_b32_e64 v244, 0, v242, s[10:11]
	v_or_b32_e32 v226, v243, v244
	v_cndmask_b32_e64 v243, v241, 0, s[12:13]
	v_cndmask_b32_e64 v244, v242, 0, s[14:15]
	v_or_b32_e32 v227, v243, v244
	v_cndmask_b32_e64 v243, 0, v241, s[12:13]
	v_cndmask_b32_e64 v244, 0, v242, s[14:15]
	v_or_b32_e32 v228, v243, v244
	v_cndmask_b32_e64 v243, v241, 0, s[16:17]
	v_cndmask_b32_e64 v244, v242, 0, s[18:19]
	v_or_b32_e32 v229, v243, v244
	v_cndmask_b32_e64 v243, 0, v241, s[16:17]
	v_cndmask_b32_e64 v244, 0, v242, s[18:19]
	v_or_b32_e32 v230, v243, v244
	v_cndmask_b32_e64 v243, v241, 0, s[6:7]
	v_cndmask_b32_e64 v244, v242, 0, s[8:9]
	v_or_b32_e32 v231, v243, v244
	v_cndmask_b32_e64 v243, 0, v241, s[6:7]
	v_cndmask_b32_e64 v244, 0, v242, s[8:9]
	v_or_b32_e32 v232, v243, v244
	v_cndmask_b32_e64 v243, 0, v241, s[2:3]
	v_cndmask_b32_e64 v244, 0, v242, s[4:5]
	v_or_b32_e32 v233, v243, v244
	v_cndmask_b32_e64 v243, v241, 0, s[2:3]
	v_cndmask_b32_e64 v244, v242, 0, s[4:5]
	v_or_b32_e32 v234, v243, v244
	v_cndmask_b32_e64 v243, v241, 0, s[22:23]
	v_cndmask_b32_e64 v244, v242, 0, s[24:25]
	v_or_b32_e32 v235, v243, v244
	v_cndmask_b32_e64 v243, 0, v241, s[22:23]
	v_cndmask_b32_e64 v244, 0, v242, s[24:25]
	v_or_b32_e32 v236, v243, v244
	v_cndmask_b32_e64 v243, v241, 0, s[26:27]
	v_cndmask_b32_e64 v244, v242, 0, s[28:29]
	v_or_b32_e32 v237, v243, v244
	v_cndmask_b32_e64 v243, 0, v241, s[26:27]
	v_cndmask_b32_e64 v244, 0, v242, s[28:29]
	v_or_b32_e32 v238, v243, v244
	v_cndmask_b32_e64 v243, v241, 0, s[30:31]
	v_cndmask_b32_e64 v244, v242, 0, s[34:35]
	v_or_b32_e32 v239, v243, v244
	v_cndmask_b32_e64 v243, 0, v241, s[30:31]
	v_cndmask_b32_e64 v244, 0, v242, s[34:35]
	v_or_b32_e32 v240, v243, v244
	s_waitcnt vmcnt(9)
	ds_write_b128 v157, v[64:67]
	s_waitcnt vmcnt(8)
	ds_write_b128 v157, v[68:71] offset:9216
	s_waitcnt lgkmcnt(0)
	s_barrier
	s_cbranch_vccnz .LBB0_701
	s_max_i32 s38, s74, 4
	s_add_i32 s38, s38, -4
	s_min_u32 s38, s38, s60
	s_mov_b32 s61, s41
	v_mov_b32_e32 v133, v113
	s_add_i32 s39, s38, 8
	v_mov_b32_e32 v0, s60
	v_cmp_lt_u64_e32 vcc, s[60:61], v[132:133]
	s_add_u32 s60, s80, s40
	v_mov_b32_e32 v1, v113
	v_cndmask_b32_e32 v2, v132, v0, vcc
	v_lshlrev_b32_e32 v0, 16, v2
	s_addc_u32 s61, s81, 0
	v_lshl_add_u64 v[0:1], s[60:61], 0, v[0:1]
	v_lshl_add_u64 v[132:133], v[0:1], 0, v[134:135]
	v_lshlrev_b32_e32 v0, 7, v2
	v_mov_b32_e32 v1, v113
	s_mul_i32 s62, s71, 0x780
	v_lshlrev_b32_e32 v2, 1, v136
	v_mov_b32_e32 v3, v113
	v_lshl_add_u64 v[0:1], s[52:53], 0, v[0:1]
	s_lshl_b32 s52, s73, 7
	v_lshl_add_u64 v[134:135], v[0:1], 0, v[2:3]
	s_add_i32 s62, s62, s52
	s_lshl_b32 s52, s74, 7
	v_mov_b32_e32 v2, v113
	s_sub_i32 s52, s62, s52
	v_mov_b32_e32 v124, v113
	v_mov_b32_e32 v125, v113
	v_mov_b32_e32 v0, v113
	v_mov_b32_e32 v1, v113
	v_mov_b64_e32 v[6:7], v[2:3]
	v_mov_b64_e32 v[10:11], v[2:3]
	v_mov_b64_e32 v[14:15], v[2:3]
	v_mov_b64_e32 v[18:19], v[2:3]
	v_mov_b64_e32 v[22:23], v[2:3]
	v_mov_b64_e32 v[26:27], v[2:3]
	v_mov_b64_e32 v[30:31], v[2:3]
	v_mov_b64_e32 v[34:35], v[2:3]
	v_mov_b64_e32 v[38:39], v[2:3]
	v_mov_b64_e32 v[42:43], v[2:3]
	v_mov_b64_e32 v[46:47], v[2:3]
	v_mov_b64_e32 v[50:51], v[2:3]
	v_mov_b64_e32 v[54:55], v[2:3]
	v_mov_b64_e32 v[58:59], v[2:3]
	v_mov_b64_e32 v[62:63], v[2:3]
	s_add_i32 s40, s73, 3
	s_add_i32 s60, s52, 0
	v_mov_b64_e32 v[4:5], v[0:1]
	v_mov_b64_e32 v[8:9], v[0:1]
	v_mov_b64_e32 v[12:13], v[0:1]
	v_mov_b64_e32 v[16:17], v[0:1]
	v_mov_b64_e32 v[20:21], v[0:1]
	v_mov_b64_e32 v[24:25], v[0:1]
	v_mov_b64_e32 v[28:29], v[0:1]
	v_mov_b64_e32 v[32:33], v[0:1]
	v_mov_b64_e32 v[36:37], v[0:1]
	v_mov_b64_e32 v[40:41], v[0:1]
	v_mov_b64_e32 v[44:45], v[0:1]
	v_mov_b64_e32 v[48:49], v[0:1]
	v_mov_b64_e32 v[52:53], v[0:1]
	v_mov_b64_e32 v[56:57], v[0:1]
	v_mov_b64_e32 v[60:61], v[0:1]
	v_mov_b64_e32 v[130:131], v[124:125]
	s_branch .LBB0_688

.LBB0_690:
	s_add_i32 s62, s40, -3
	s_cmp_ge_u32 s62, s38
	s_cselect_b64 s[52:53], -1, 0
	s_cmp_lt_u32 s62, s39
	s_cselect_b64 s[74:75], -1, 0
	s_and_b64 s[52:53], s[52:53], s[74:75]
	s_andn2_b64 vcc, exec, s[52:53]
	s_cbranch_vccnz .LBB0_692
	v_add_u32_e32 v178, v150, v149
	v_add_u32_e32 v181, 0x2000, v178
	v_add_u32_e32 v218, 0x2800, v178
	v_add_u32_e32 v219, 0x3000, v178
	v_add_u32_e32 v178, v150, v151
	v_add_u32_e32 v119, v148, v149
	v_add_u32_e32 v136, s60, v152
	v_add_u32_sdwa v163, s60, v144 dst_sel:DWORD dst_unused:UNUSED_PAD src0_sel:DWORD src1_sel:BYTE_2
	v_add_u32_sdwa v165, s60, v144 dst_sel:DWORD dst_unused:UNUSED_PAD src0_sel:DWORD src1_sel:BYTE_3
	v_add_u32_e32 v220, 0x2000, v178
	v_add_u32_sdwa v179, s60, v142 dst_sel:DWORD dst_unused:UNUSED_PAD src0_sel:DWORD src1_sel:BYTE_1
	ds_read_b128 v[158:161], v119
	ds_read_b128 v[166:169], v119 offset:64
	ds_read_b128 v[170:173], v119 offset:2304
	ds_read_b128 v[174:177], v119 offset:2368
	v_add_u32_e32 v162, s60, v153
	ds_read_b64 v[182:183], v181 offset:1024
	ds_read_b64 v[184:185], v181 offset:1056
	ds_read_b64 v[186:187], v218 offset:1280
	ds_read_b64 v[188:189], v218 offset:1312
	ds_read_b64 v[190:191], v219 offset:1536
	ds_read_b64 v[192:193], v219 offset:1568
	ds_read_b64 v[194:195], v220 offset:1024
	ds_read_b64 v[196:197], v220 offset:1056
	ds_read_b128 v[198:201], v119 offset:1152
	ds_read_b128 v[202:205], v119 offset:1216
	ds_read_b128 v[206:209], v119 offset:3456
	ds_read_b128 v[210:213], v119 offset:3520
	v_add_u32_e32 v178, s60, v155
	v_add_u32_sdwa v214, s60, v143 dst_sel:DWORD dst_unused:UNUSED_PAD src0_sel:DWORD src1_sel:BYTE_2
	v_add_u32_sdwa v215, s60, v143 dst_sel:DWORD dst_unused:UNUSED_PAD src0_sel:DWORD src1_sel:BYTE_3
	ds_read_b32 v136, v136 offset:41856
	ds_read_b32 v216, v162 offset:41856
	ds_read_b32 v163, v163 offset:41856
	ds_read_b32 v165, v165 offset:41856
	ds_read_b32 v217, v178 offset:41856
	ds_read_b32 v179, v179 offset:41856
	ds_read_b32 v221, v214 offset:41856
	ds_read_b32 v222, v215 offset:41856
	s_setprio 1
	s_waitcnt vmcnt(7) lgkmcnt(15)
	v_mfma_f32_16x16x32_bf16 v[158:161], v[158:161], v[80:83], 0
	s_waitcnt vmcnt(6)
	v_mfma_f32_16x16x32_bf16 v[158:161], v[166:169], v[84:87], v[158:161]
	v_mfma_f32_16x16x32_bf16 v[166:169], v[170:173], v[80:83], 0
	v_mfma_f32_16x16x32_bf16 v[166:169], v[174:177], v[84:87], v[166:169]
	s_setprio 0
	s_nop 6
	v_cndmask_b32_e64 v158, v166, v158, s[20:21]
	s_waitcnt lgkmcnt(7)
	v_add_f32_e32 v136, v136, v158
	v_exp_f32_e32 v162, v136
	v_cndmask_b32_e64 v136, v159, v167, s[10:11]
	v_cndmask_b32_e64 v159, v160, v168, s[12:13]
	s_waitcnt lgkmcnt(5)
	v_add_f32_e32 v159, v163, v159
	v_add_f32_e32 v136, v216, v136
	v_exp_f32_e32 v214, v159
	v_cndmask_b32_e64 v159, v161, v169, s[14:15]
	v_exp_f32_e32 v178, v136
	s_waitcnt lgkmcnt(4)
	v_add_f32_e32 v159, v165, v159
	v_exp_f32_e32 v216, v159
	s_nop 0
	v_cvt_pk_bf16_f32 v243, v162, v178
	v_cvt_pk_bf16_f32 v244, v214, v216
	v_and_b32_e32 v158, v243, v225
	v_and_b32_e32 v160, v243, v226
	v_and_b32_e32 v159, v244, v227
	v_and_b32_e32 v161, v244, v228
	s_setprio 1
	v_mfma_f32_16x16x32_bf16 v[60:63], v[182:185], v[158:161], v[60:63]
	v_mfma_f32_16x16x32_bf16 v[56:59], v[186:189], v[158:161], v[56:59]
	v_mfma_f32_16x16x32_bf16 v[52:55], v[190:193], v[158:161], v[52:55]
	v_mfma_f32_16x16x32_bf16 v[48:51], v[194:197], v[158:161], v[48:51]
	s_setprio 0
	ds_read_b64 v[158:159], v181 offset:1040
	ds_read_b64 v[160:161], v181 offset:1072
	ds_read_b64 v[166:167], v218 offset:1296
	ds_read_b64 v[168:169], v218 offset:1328
	ds_read_b64 v[170:171], v219 offset:1552
	ds_read_b64 v[172:173], v219 offset:1584
	ds_read_b64 v[174:175], v220 offset:1040
	ds_read_b64 v[176:177], v220 offset:1072
	ds_read_b128 v[182:185], v119 offset:3456
	ds_read_b128 v[186:189], v119 offset:3520
	ds_read_b128 v[190:193], v119 offset:5760
	ds_read_b128 v[194:197], v119 offset:5824
	v_add_u32_e32 v136, s60, v156
	v_add_u32_sdwa v165, s60, v141 dst_sel:DWORD dst_unused:UNUSED_PAD src0_sel:DWORD src1_sel:BYTE_2
	v_add_u32_sdwa v163, s60, v140 dst_sel:DWORD dst_unused:UNUSED_PAD src0_sel:DWORD src1_sel:BYTE_1
	v_add_u32_sdwa v215, s60, v141 dst_sel:DWORD dst_unused:UNUSED_PAD src0_sel:DWORD src1_sel:BYTE_3
	ds_read_b32 v136, v136 offset:41856
	ds_read_b32 v223, v163 offset:41856
	ds_read_b32 v165, v165 offset:41856
	ds_read_b32 v224, v215 offset:41856
	s_setprio 1
	s_waitcnt vmcnt(5)
	v_mfma_f32_16x16x32_bf16 v[198:201], v[198:201], v[88:91], 0
	s_waitcnt vmcnt(4)
	v_mfma_f32_16x16x32_bf16 v[198:201], v[202:205], v[92:95], v[198:201]
	v_mfma_f32_16x16x32_bf16 v[202:205], v[206:209], v[88:91], 0
	v_mfma_f32_16x16x32_bf16 v[202:205], v[210:213], v[92:95], v[202:205]
	s_setprio 0
	s_nop 6
	v_cndmask_b32_e64 v163, v198, v202, s[16:17]
	s_waitcnt lgkmcnt(15)
	v_add_f32_e32 v163, v217, v163
	v_cndmask_b32_e64 v198, v199, v203, s[18:19]
	v_cndmask_b32_e64 v200, v200, v204, s[6:7]
	v_exp_f32_e32 v163, v163
	v_add_f32_e32 v179, v179, v198
	s_waitcnt lgkmcnt(15)
	v_add_f32_e32 v200, v221, v200
	v_exp_f32_e32 v179, v179
	v_exp_f32_e32 v215, v200
	v_cndmask_b32_e64 v200, v201, v205, s[8:9]
	s_waitcnt lgkmcnt(15)
	v_add_f32_e32 v200, v222, v200
	v_exp_f32_e32 v217, v200
	s_nop 0
	v_cvt_pk_bf16_f32 v243, v163, v179
	v_cvt_pk_bf16_f32 v244, v215, v217
	v_pk_add_f32 v[162:163], v[162:163], 0 op_sel_hi:[1,0]
	v_pk_add_f32 v[162:163], v[178:179], v[162:163]
	v_pk_add_f32 v[162:163], v[214:215], v[162:163]
	v_pk_add_f32 v[162:163], v[216:217], v[162:163]
	v_pk_add_f32 v[130:131], v[130:131], v[162:163]
	v_and_b32_e32 v198, v243, v229
	v_and_b32_e32 v200, v243, v230
	v_and_b32_e32 v199, v244, v231
	v_and_b32_e32 v201, v244, v232
	s_setprio 1
	s_waitcnt lgkmcnt(14)
	v_mfma_f32_16x16x32_bf16 v[44:47], v[158:161], v[198:201], v[44:47]
	s_waitcnt lgkmcnt(12)
	v_mfma_f32_16x16x32_bf16 v[40:43], v[166:169], v[198:201], v[40:43]
	s_waitcnt lgkmcnt(10)
	v_mfma_f32_16x16x32_bf16 v[36:39], v[170:173], v[198:201], v[36:39]
	s_waitcnt lgkmcnt(8)
	v_mfma_f32_16x16x32_bf16 v[32:35], v[174:177], v[198:201], v[32:35]
	s_setprio 0
	ds_read_b64 v[158:159], v181 offset:1072
	ds_read_b64 v[160:161], v181 offset:1104
	ds_read_b64 v[166:167], v218 offset:1328
	ds_read_b64 v[168:169], v218 offset:1360
	ds_read_b64 v[170:171], v219 offset:1584
	ds_read_b64 v[172:173], v219 offset:1616
	ds_read_b64 v[174:175], v220 offset:1072
	ds_read_b64 v[176:177], v220 offset:1104
	ds_read_b128 v[198:201], v119 offset:4608
	ds_read_b128 v[202:205], v119 offset:4672
	v_add_u32_e32 v119, v148, v151
	ds_read_b128 v[206:209], v119
	ds_read_b128 v[210:213], v119 offset:64
	v_add_u32_e32 v119, s60, v154
	v_add_u32_sdwa v162, s60, v145 dst_sel:DWORD dst_unused:UNUSED_PAD src0_sel:DWORD src1_sel:BYTE_1
	v_add_u32_sdwa v163, s60, v146 dst_sel:DWORD dst_unused:UNUSED_PAD src0_sel:DWORD src1_sel:BYTE_2
	v_add_u32_sdwa v178, s60, v146 dst_sel:DWORD dst_unused:UNUSED_PAD src0_sel:DWORD src1_sel:BYTE_3
	ds_read_b32 v119, v119 offset:41856
	ds_read_b32 v179, v162 offset:41856
	ds_read_b32 v214, v163 offset:41856
	ds_read_b32 v215, v178 offset:41856
	s_setprio 1
	s_waitcnt vmcnt(3) lgkmcnt(15)
	v_mfma_f32_16x16x32_bf16 v[182:185], v[182:185], v[96:99], 0
	s_waitcnt vmcnt(2)
	v_mfma_f32_16x16x32_bf16 v[182:185], v[186:189], v[100:103], v[182:185]
	v_mfma_f32_16x16x32_bf16 v[186:189], v[190:193], v[96:99], 0
	v_mfma_f32_16x16x32_bf16 v[186:189], v[194:197], v[100:103], v[186:189]
	s_setprio 0
	s_nop 6
	v_cndmask_b32_e64 v162, v186, v182, s[2:3]
	v_add_f32_e32 v136, v136, v162
	v_exp_f32_e32 v162, v136
	v_cndmask_b32_e64 v136, v187, v183, s[4:5]
	v_cndmask_b32_e64 v183, v184, v188, s[22:23]
	s_waitcnt lgkmcnt(15)
	v_add_f32_e32 v165, v165, v183
	v_exp_f32_e32 v190, v165
	v_cndmask_b32_e64 v165, v185, v189, s[24:25]
	v_add_f32_e32 v136, v223, v136
	s_waitcnt lgkmcnt(15)
	v_add_f32_e32 v165, v224, v165
	v_exp_f32_e32 v178, v136
	v_exp_f32_e32 v192, v165
	s_nop 0
	v_cvt_pk_bf16_f32 v243, v162, v178
	v_cvt_pk_bf16_f32 v244, v190, v192
	v_and_b32_e32 v182, v243, v233
	v_and_b32_e32 v184, v243, v234
	v_and_b32_e32 v183, v244, v235
	v_and_b32_e32 v185, v244, v236
	s_setprio 1
	s_waitcnt lgkmcnt(14)
	v_mfma_f32_16x16x32_bf16 v[28:31], v[158:161], v[182:185], v[28:31]
	s_waitcnt lgkmcnt(12)
	v_mfma_f32_16x16x32_bf16 v[24:27], v[166:169], v[182:185], v[24:27]
	s_waitcnt lgkmcnt(10)
	v_mfma_f32_16x16x32_bf16 v[20:23], v[170:173], v[182:185], v[20:23]
	s_waitcnt lgkmcnt(8)
	v_mfma_f32_16x16x32_bf16 v[16:19], v[174:177], v[182:185], v[16:19]
	s_setprio 0
	ds_read_b64 v[158:159], v220 offset:1088
	ds_read_b64 v[160:161], v220 offset:1120
	ds_read_b64 v[166:167], v219 offset:1600
	ds_read_b64 v[168:169], v219 offset:1632
	ds_read_b64 v[170:171], v218 offset:1344
	ds_read_b64 v[172:173], v218 offset:1376
	ds_read_b64 v[174:175], v181 offset:1088
	ds_read_b64 v[176:177], v181 offset:1120
	s_setprio 1
	s_waitcnt vmcnt(1) lgkmcnt(15)
	v_mfma_f32_16x16x32_bf16 v[182:185], v[198:201], v[104:107], 0
	s_waitcnt lgkmcnt(13)
	v_mfma_f32_16x16x32_bf16 v[186:189], v[206:209], v[104:107], 0
	s_waitcnt vmcnt(0)
	v_mfma_f32_16x16x32_bf16 v[182:185], v[202:205], v[108:111], v[182:185]
	s_waitcnt lgkmcnt(12)
	v_mfma_f32_16x16x32_bf16 v[186:189], v[210:213], v[108:111], v[186:189]
	s_setprio 0
	s_nop 6
	v_cndmask_b32_e64 v136, v182, v186, s[26:27]
	s_waitcnt lgkmcnt(11)
	v_add_f32_e32 v119, v119, v136
	v_exp_f32_e32 v163, v119
	v_cndmask_b32_e64 v119, v183, v187, s[28:29]
	v_cndmask_b32_e64 v181, v184, v188, s[30:31]
	s_waitcnt lgkmcnt(10)
	v_add_f32_e32 v119, v179, v119
	s_waitcnt lgkmcnt(9)
	v_add_f32_e32 v181, v214, v181
	v_exp_f32_e32 v179, v119
	v_exp_f32_e32 v191, v181
	v_cndmask_b32_e64 v181, v185, v189, s[34:35]
	s_waitcnt lgkmcnt(8)
	v_add_f32_e32 v181, v215, v181
	v_exp_f32_e32 v193, v181
	s_nop 0
	v_cvt_pk_bf16_f32 v243, v163, v179
	v_cvt_pk_bf16_f32 v244, v191, v193
	v_pk_add_f32 v[162:163], v[162:163], 0 op_sel_hi:[1,0]
	v_pk_add_f32 v[162:163], v[178:179], v[162:163]
	v_pk_add_f32 v[162:163], v[190:191], v[162:163]
	v_pk_add_f32 v[162:163], v[192:193], v[162:163]
	v_pk_add_f32 v[124:125], v[124:125], v[162:163]
	v_and_b32_e32 v182, v243, v237
	v_and_b32_e32 v184, v243, v238
	v_and_b32_e32 v183, v244, v239
	v_and_b32_e32 v185, v244, v240
	s_setprio 1
	s_waitcnt lgkmcnt(0)
	v_mfma_f32_16x16x32_bf16 v[12:15], v[174:177], v[182:185], v[12:15]
	v_mfma_f32_16x16x32_bf16 v[8:11], v[170:173], v[182:185], v[8:11]
	v_mfma_f32_16x16x32_bf16 v[4:7], v[166:169], v[182:185], v[4:7]
	v_mfma_f32_16x16x32_bf16 v[0:3], v[158:161], v[182:185], v[0:3]
	s_setprio 0

.LBB0_697:
	s_add_i32 s52, s40, -2
	s_cmp_ge_u32 s52, s38
	s_cselect_b64 s[62:63], -1, 0
	s_cmp_lt_u32 s52, s39
	s_cselect_b64 s[74:75], -1, 0
	s_and_b64 s[62:63], s[62:63], s[74:75]
	s_andn2_b64 vcc, exec, s[62:63]
	s_cbranch_vccnz .LBB0_699
	v_add_u32_e32 v178, v150, v149
	v_add_u32_e32 v181, 0x6800, v178
	v_add_u32_e32 v218, 0x7000, v178
	v_add_u32_e32 v219, 0x7800, v178
	v_add_u32_e32 v178, v150, v151
	v_add_u32_e32 v119, v148, v149
	v_add_u32_e32 v136, s60, v152
	v_add_u32_sdwa v163, s60, v144 dst_sel:DWORD dst_unused:UNUSED_PAD src0_sel:DWORD src1_sel:BYTE_2
	v_add_u32_sdwa v165, s60, v144 dst_sel:DWORD dst_unused:UNUSED_PAD src0_sel:DWORD src1_sel:BYTE_3
	v_add_u32_e32 v220, 0x6800, v178
	v_add_u32_sdwa v179, s60, v142 dst_sel:DWORD dst_unused:UNUSED_PAD src0_sel:DWORD src1_sel:BYTE_1
	ds_read_b128 v[158:161], v119 offset:18432
	ds_read_b128 v[166:169], v119 offset:18496
	ds_read_b128 v[170:173], v119 offset:20736
	ds_read_b128 v[174:177], v119 offset:20800
	v_add_u32_e32 v162, s60, v153
	ds_read_b64 v[182:183], v181 offset:1024
	ds_read_b64 v[184:185], v181 offset:1056
	ds_read_b64 v[186:187], v218 offset:1280
	ds_read_b64 v[188:189], v218 offset:1312
	ds_read_b64 v[190:191], v219 offset:1536
	ds_read_b64 v[192:193], v219 offset:1568
	ds_read_b64 v[194:195], v220 offset:1024
	ds_read_b64 v[196:197], v220 offset:1056
	ds_read_b128 v[198:201], v119 offset:19584
	ds_read_b128 v[202:205], v119 offset:19648
	ds_read_b128 v[206:209], v119 offset:21888
	ds_read_b128 v[210:213], v119 offset:21952
	v_add_u32_e32 v178, s60, v155
	v_add_u32_sdwa v214, s60, v143 dst_sel:DWORD dst_unused:UNUSED_PAD src0_sel:DWORD src1_sel:BYTE_2
	v_add_u32_sdwa v215, s60, v143 dst_sel:DWORD dst_unused:UNUSED_PAD src0_sel:DWORD src1_sel:BYTE_3
	ds_read_b32 v136, v136 offset:41984
	ds_read_b32 v216, v162 offset:41984
	ds_read_b32 v163, v163 offset:41984
	ds_read_b32 v165, v165 offset:41984
	ds_read_b32 v217, v178 offset:41984
	ds_read_b32 v179, v179 offset:41984
	ds_read_b32 v221, v214 offset:41984
	ds_read_b32 v222, v215 offset:41984
	s_setprio 1
	s_waitcnt vmcnt(7) lgkmcnt(15)
	v_mfma_f32_16x16x32_bf16 v[158:161], v[158:161], v[80:83], 0
	s_waitcnt vmcnt(6)
	v_mfma_f32_16x16x32_bf16 v[158:161], v[166:169], v[84:87], v[158:161]
	v_mfma_f32_16x16x32_bf16 v[166:169], v[170:173], v[80:83], 0
	v_mfma_f32_16x16x32_bf16 v[166:169], v[174:177], v[84:87], v[166:169]
	s_setprio 0
	s_nop 6
	v_cndmask_b32_e64 v158, v166, v158, s[20:21]
	s_waitcnt lgkmcnt(7)
	v_add_f32_e32 v136, v136, v158
	v_exp_f32_e32 v162, v136
	v_cndmask_b32_e64 v136, v159, v167, s[10:11]
	v_cndmask_b32_e64 v159, v160, v168, s[12:13]
	s_waitcnt lgkmcnt(5)
	v_add_f32_e32 v159, v163, v159
	v_add_f32_e32 v136, v216, v136
	v_exp_f32_e32 v214, v159
	v_cndmask_b32_e64 v159, v161, v169, s[14:15]
	v_exp_f32_e32 v178, v136
	s_waitcnt lgkmcnt(4)
	v_add_f32_e32 v159, v165, v159
	v_exp_f32_e32 v216, v159
	s_nop 0
	v_cvt_pk_bf16_f32 v243, v162, v178
	v_cvt_pk_bf16_f32 v244, v214, v216
	v_and_b32_e32 v158, v243, v225
	v_and_b32_e32 v160, v243, v226
	v_and_b32_e32 v159, v244, v227
	v_and_b32_e32 v161, v244, v228
	s_setprio 1
	v_mfma_f32_16x16x32_bf16 v[60:63], v[182:185], v[158:161], v[60:63]
	v_mfma_f32_16x16x32_bf16 v[56:59], v[186:189], v[158:161], v[56:59]
	v_mfma_f32_16x16x32_bf16 v[52:55], v[190:193], v[158:161], v[52:55]
	v_mfma_f32_16x16x32_bf16 v[48:51], v[194:197], v[158:161], v[48:51]
	s_setprio 0
	ds_read_b64 v[158:159], v181 offset:1040
	ds_read_b64 v[160:161], v181 offset:1072
	ds_read_b64 v[166:167], v218 offset:1296
	ds_read_b64 v[168:169], v218 offset:1328
	ds_read_b64 v[170:171], v219 offset:1552
	ds_read_b64 v[172:173], v219 offset:1584
	ds_read_b64 v[174:175], v220 offset:1040
	ds_read_b64 v[176:177], v220 offset:1072
	ds_read_b128 v[182:185], v119 offset:21888
	ds_read_b128 v[186:189], v119 offset:21952
	ds_read_b128 v[190:193], v119 offset:24192
	ds_read_b128 v[194:197], v119 offset:24256
	v_add_u32_e32 v136, s60, v156
	v_add_u32_sdwa v165, s60, v141 dst_sel:DWORD dst_unused:UNUSED_PAD src0_sel:DWORD src1_sel:BYTE_2
	v_add_u32_sdwa v163, s60, v140 dst_sel:DWORD dst_unused:UNUSED_PAD src0_sel:DWORD src1_sel:BYTE_1
	v_add_u32_sdwa v215, s60, v141 dst_sel:DWORD dst_unused:UNUSED_PAD src0_sel:DWORD src1_sel:BYTE_3
	ds_read_b32 v136, v136 offset:41984
	ds_read_b32 v223, v163 offset:41984
	ds_read_b32 v165, v165 offset:41984
	ds_read_b32 v224, v215 offset:41984
	s_setprio 1
	s_waitcnt vmcnt(5)
	v_mfma_f32_16x16x32_bf16 v[198:201], v[198:201], v[88:91], 0
	s_waitcnt vmcnt(4)
	v_mfma_f32_16x16x32_bf16 v[198:201], v[202:205], v[92:95], v[198:201]
	v_mfma_f32_16x16x32_bf16 v[202:205], v[206:209], v[88:91], 0
	v_mfma_f32_16x16x32_bf16 v[202:205], v[210:213], v[92:95], v[202:205]
	s_setprio 0
	s_nop 6
	v_cndmask_b32_e64 v163, v198, v202, s[16:17]
	s_waitcnt lgkmcnt(15)
	v_add_f32_e32 v163, v217, v163
	v_cndmask_b32_e64 v198, v199, v203, s[18:19]
	v_cndmask_b32_e64 v200, v200, v204, s[6:7]
	v_exp_f32_e32 v163, v163
	v_add_f32_e32 v179, v179, v198
	s_waitcnt lgkmcnt(15)
	v_add_f32_e32 v200, v221, v200
	v_exp_f32_e32 v179, v179
	v_exp_f32_e32 v215, v200
	v_cndmask_b32_e64 v200, v201, v205, s[8:9]
	s_waitcnt lgkmcnt(15)
	v_add_f32_e32 v200, v222, v200
	v_exp_f32_e32 v217, v200
	s_nop 0
	v_cvt_pk_bf16_f32 v243, v163, v179
	v_cvt_pk_bf16_f32 v244, v215, v217
	v_pk_add_f32 v[162:163], v[162:163], 0 op_sel_hi:[1,0]
	v_pk_add_f32 v[162:163], v[178:179], v[162:163]
	v_pk_add_f32 v[162:163], v[214:215], v[162:163]
	v_pk_add_f32 v[162:163], v[216:217], v[162:163]
	v_pk_add_f32 v[130:131], v[130:131], v[162:163]
	v_and_b32_e32 v198, v243, v229
	v_and_b32_e32 v200, v243, v230
	v_and_b32_e32 v199, v244, v231
	v_and_b32_e32 v201, v244, v232
	s_setprio 1
	s_waitcnt lgkmcnt(14)
	v_mfma_f32_16x16x32_bf16 v[44:47], v[158:161], v[198:201], v[44:47]
	s_waitcnt lgkmcnt(12)
	v_mfma_f32_16x16x32_bf16 v[40:43], v[166:169], v[198:201], v[40:43]
	s_waitcnt lgkmcnt(10)
	v_mfma_f32_16x16x32_bf16 v[36:39], v[170:173], v[198:201], v[36:39]
	s_waitcnt lgkmcnt(8)
	v_mfma_f32_16x16x32_bf16 v[32:35], v[174:177], v[198:201], v[32:35]
	s_setprio 0
	ds_read_b64 v[158:159], v181 offset:1072
	ds_read_b64 v[160:161], v181 offset:1104
	ds_read_b64 v[166:167], v218 offset:1328
	ds_read_b64 v[168:169], v218 offset:1360
	ds_read_b64 v[170:171], v219 offset:1584
	ds_read_b64 v[172:173], v219 offset:1616
	ds_read_b64 v[174:175], v220 offset:1072
	ds_read_b64 v[176:177], v220 offset:1104
	ds_read_b128 v[198:201], v119 offset:23040
	ds_read_b128 v[202:205], v119 offset:23104
	v_add_u32_e32 v119, v148, v151
	ds_read_b128 v[206:209], v119 offset:18432
	ds_read_b128 v[210:213], v119 offset:18496
	v_add_u32_e32 v119, s60, v154
	v_add_u32_sdwa v162, s60, v145 dst_sel:DWORD dst_unused:UNUSED_PAD src0_sel:DWORD src1_sel:BYTE_1
	v_add_u32_sdwa v163, s60, v146 dst_sel:DWORD dst_unused:UNUSED_PAD src0_sel:DWORD src1_sel:BYTE_2
	v_add_u32_sdwa v178, s60, v146 dst_sel:DWORD dst_unused:UNUSED_PAD src0_sel:DWORD src1_sel:BYTE_3
	ds_read_b32 v119, v119 offset:41984
	ds_read_b32 v179, v162 offset:41984
	ds_read_b32 v214, v163 offset:41984
	ds_read_b32 v215, v178 offset:41984
	s_setprio 1
	s_waitcnt vmcnt(3) lgkmcnt(15)
	v_mfma_f32_16x16x32_bf16 v[182:185], v[182:185], v[96:99], 0
	s_waitcnt vmcnt(2)
	v_mfma_f32_16x16x32_bf16 v[182:185], v[186:189], v[100:103], v[182:185]
	v_mfma_f32_16x16x32_bf16 v[186:189], v[190:193], v[96:99], 0
	v_mfma_f32_16x16x32_bf16 v[186:189], v[194:197], v[100:103], v[186:189]
	s_setprio 0
	s_nop 6
	v_cndmask_b32_e64 v162, v186, v182, s[2:3]
	v_add_f32_e32 v136, v136, v162
	v_exp_f32_e32 v162, v136
	v_cndmask_b32_e64 v136, v187, v183, s[4:5]
	v_cndmask_b32_e64 v183, v184, v188, s[22:23]
	s_waitcnt lgkmcnt(15)
	v_add_f32_e32 v165, v165, v183
	v_exp_f32_e32 v190, v165
	v_cndmask_b32_e64 v165, v185, v189, s[24:25]
	v_add_f32_e32 v136, v223, v136
	s_waitcnt lgkmcnt(15)
	v_add_f32_e32 v165, v224, v165
	v_exp_f32_e32 v178, v136
	v_exp_f32_e32 v192, v165
	s_nop 0
	v_cvt_pk_bf16_f32 v243, v162, v178
	v_cvt_pk_bf16_f32 v244, v190, v192
	v_and_b32_e32 v182, v243, v233
	v_and_b32_e32 v184, v243, v234
	v_and_b32_e32 v183, v244, v235
	v_and_b32_e32 v185, v244, v236
	s_setprio 1
	s_waitcnt lgkmcnt(14)
	v_mfma_f32_16x16x32_bf16 v[28:31], v[158:161], v[182:185], v[28:31]
	s_waitcnt lgkmcnt(12)
	v_mfma_f32_16x16x32_bf16 v[24:27], v[166:169], v[182:185], v[24:27]
	s_waitcnt lgkmcnt(10)
	v_mfma_f32_16x16x32_bf16 v[20:23], v[170:173], v[182:185], v[20:23]
	s_waitcnt lgkmcnt(8)
	v_mfma_f32_16x16x32_bf16 v[16:19], v[174:177], v[182:185], v[16:19]
	s_setprio 0
	ds_read_b64 v[158:159], v220 offset:1088
	ds_read_b64 v[160:161], v220 offset:1120
	ds_read_b64 v[166:167], v219 offset:1600
	ds_read_b64 v[168:169], v219 offset:1632
	ds_read_b64 v[170:171], v218 offset:1344
	ds_read_b64 v[172:173], v218 offset:1376
	ds_read_b64 v[174:175], v181 offset:1088
	ds_read_b64 v[176:177], v181 offset:1120
	s_setprio 1
	s_waitcnt vmcnt(1) lgkmcnt(15)
	v_mfma_f32_16x16x32_bf16 v[182:185], v[198:201], v[104:107], 0
	s_waitcnt lgkmcnt(13)
	v_mfma_f32_16x16x32_bf16 v[186:189], v[206:209], v[104:107], 0
	s_waitcnt vmcnt(0)
	v_mfma_f32_16x16x32_bf16 v[182:185], v[202:205], v[108:111], v[182:185]
	s_waitcnt lgkmcnt(12)
	v_mfma_f32_16x16x32_bf16 v[186:189], v[210:213], v[108:111], v[186:189]
	s_setprio 0
	s_nop 6
	v_cndmask_b32_e64 v136, v182, v186, s[26:27]
	s_waitcnt lgkmcnt(11)
	v_add_f32_e32 v119, v119, v136
	v_exp_f32_e32 v163, v119
	v_cndmask_b32_e64 v119, v183, v187, s[28:29]
	v_cndmask_b32_e64 v181, v184, v188, s[30:31]
	s_waitcnt lgkmcnt(10)
	v_add_f32_e32 v119, v179, v119
	s_waitcnt lgkmcnt(9)
	v_add_f32_e32 v181, v214, v181
	v_exp_f32_e32 v179, v119
	v_exp_f32_e32 v191, v181
	v_cndmask_b32_e64 v181, v185, v189, s[34:35]
	s_waitcnt lgkmcnt(8)
	v_add_f32_e32 v181, v215, v181
	v_exp_f32_e32 v193, v181
	s_nop 0
	v_cvt_pk_bf16_f32 v243, v163, v179
	v_cvt_pk_bf16_f32 v244, v191, v193
	v_pk_add_f32 v[162:163], v[162:163], 0 op_sel_hi:[1,0]
	v_pk_add_f32 v[162:163], v[178:179], v[162:163]
	v_pk_add_f32 v[162:163], v[190:191], v[162:163]
	v_pk_add_f32 v[162:163], v[192:193], v[162:163]
	v_pk_add_f32 v[124:125], v[124:125], v[162:163]
	v_and_b32_e32 v182, v243, v237
	v_and_b32_e32 v184, v243, v238
	v_and_b32_e32 v183, v244, v239
	v_and_b32_e32 v185, v244, v240
	s_setprio 1
	s_waitcnt lgkmcnt(0)
	v_mfma_f32_16x16x32_bf16 v[12:15], v[174:177], v[182:185], v[12:15]
	v_mfma_f32_16x16x32_bf16 v[8:11], v[170:173], v[182:185], v[8:11]
	v_mfma_f32_16x16x32_bf16 v[4:7], v[166:169], v[182:185], v[4:7]
	v_mfma_f32_16x16x32_bf16 v[0:3], v[158:161], v[182:185], v[0:3]
	s_setprio 0
